# G1: the three chunks K-row loads issued together (counted vmcnt) instead of load-wait-write x3; combine: the four hyena-output loads per tile issued together
# speedup vs baseline: 1.0245x; 1.0031x over previous
; #define LAS __attribute__((address_space(3)))
; __device__ __forceinline__ float softplusf(float v) { return fmaxf(v, 0.f) + log1pf(__expf(-fabsf(v))); }
; __device__ NOINL void g1_phase(const LAS Params* lp, int l, LAS unsigned char* lds) {
;     ...
;     for (int it = blockIdx.x; it < NB * 4 * 12; it += gridDim.x) {
;         const int b = it / 48, h = (it / 12) & 3, c3 = it % 12;
;         __syncthreads();
;         {
;             const int tk = tid >> 3, cg8 = tid & 7;
; #pragma unroll
;             for (int s = 0; s < 3; ++s) {
;                 int row0, t0, L; chunk_geom(b, c3 * 3 + s, row0, t0, L);
;                 const bf16_t* src = p.proj + (size_t)(row0 + tk) * 3072 + 512 + h * 128 + cg8 * 16;
;                 LAS bf16_t* Kn = (LAS bf16_t*)(lds + s * SLOT);
;                 *(LAS u32x4*)(Kn + tk * 136 + cg8 * 16) = *(const u32x4*)src; *(LAS u32x4*)(Kn + tk * 136 + cg8 * 16 + 8) = *(const u32x4*)(src + 8);
;             }
;         }
;         if (w < 6) {
;             const int s = w >> 1, dir = w & 1, tk = dir ? 63 - lane : lane;
;             int row0, t0, L; chunk_geom(b, c3 * 3 + s, row0, t0, L);
;             const float a = p.ab[(size_t)(row0 + tk) * 16 + dir * 4 + h], bb = p.ab[(size_t)(row0 + tk) * 16 + 8 + dir * 4 + h];
;             float g = -__expf(p.gdn_a_log[l * 8 + dir * 4 + h]) * softplusf(a + p.gdn_dt_bias[l * 8 + dir * 4 + h]);
.LBB0_1045:
	s_mul_hi_i32 s0, s66, 0x2aaaaaab
	s_ashr_i32 s67, s0, 3
	s_lshr_b32 s1, s0, 31
	s_ashr_i32 s0, s0, 1
	s_add_i32 s0, s0, s1
	s_add_i32 s67, s67, s1
	s_and_b32 s68, s0, 3
	s_mul_i32 s0, s0, 12
	s_sub_i32 s3, s66, s0
	s_lshl_b32 s0, s67, 11
	s_lshl_b32 s1, s67, 8
	s_addk_i32 s0, 0xff00
	s_add_i32 s1, s1, 0x8000
	s_cmp_lt_i32 s3, 2
	s_mul_i32 s4, s3, 0xc0
	s_cselect_b32 s5, s1, s0
	v_add_u32_e32 v99, s4, v21
	v_add_u32_e32 v8, s5, v99
	v_mov_b64_e32 v[18:19], s[60:61]
	v_mad_i64_i32 v[8:9], s[4:5], v8, s81, v[18:19]
	s_lshl_b32 s6, s68, 8
	v_lshl_add_u64 v[8:9], v[8:9], 0, s[6:7]
	v_lshl_add_u64 v[100:101], v[8:9], 0, v[0:1]
	s_barrier
	s_cmp_lt_i32 s3, 1
	s_mul_i32 s18, s3, 3
	s_cselect_b32 s3, s1, s0
	global_load_dwordx4 v[166:169], v[100:101], off offset:1040
	global_load_dwordx4 v[170:173], v[100:101], off offset:1024
	v_add_u32_e32 v165, s3, v99
	v_add_u32_e32 v174, 64, v165
	v_mad_i64_i32 v[176:177], s[4:5], v174, s81, v[18:19]
	v_lshl_add_u64 v[174:175], v[176:177], 0, s[6:7]
	v_lshl_add_u64 v[176:177], v[174:175], 0, v[0:1]
	global_load_dwordx4 v[178:181], v[176:177], off offset:1040
	global_load_dwordx4 v[186:189], v[176:177], off offset:1024
	v_add_u32_e32 v174, 0x80, v165
	v_mad_i64_i32 v[176:177], s[4:5], v174, s81, v[18:19]
	v_lshl_add_u64 v[174:175], v[176:177], 0, s[6:7]
	v_lshl_add_u64 v[176:177], v[174:175], 0, v[0:1]
	global_load_dwordx4 v[190:193], v[176:177], off offset:1040
	global_load_dwordx4 v[194:197], v[176:177], off offset:1024
	s_nop 0
	s_waitcnt vmcnt(4)
	ds_write_b128 v22, v[170:173]
	ds_write_b128 v22, v[166:169] offset:16
	s_nop 0
	s_waitcnt vmcnt(2)
	ds_write_b128 v22, v[186:189] offset:51200
	ds_write_b128 v22, v[178:181] offset:51216
	v_add_u32_e32 v18, s18, v23
	v_ashrrev_i32_e32 v19, 31, v18
	s_waitcnt vmcnt(0)
	ds_write_b128 v29, v[194:197]
	ds_write_b128 v30, v[190:193]
	s_and_saveexec_b64 s[40:41], vcc
	s_cbranch_execz .LBB0_1047
	v_cmp_gt_i32_e64 s[56:57], 4, v18
	v_mov_b32_e32 v8, s0
	v_mov_b32_e32 v9, s1
	v_cndmask_b32_e64 v8, v8, v9, s[56:57]
	v_lshl_add_u32 v8, v18, 6, v8
	v_or_b32_e32 v8, v8, v24
	v_ashrrev_i32_e32 v9, 31, v8
	v_lshlrev_b64 v[8:9], 6, v[8:9]
	v_or_b32_e32 v10, s68, v25
	v_mov_b32_e32 v11, v1
	v_lshl_add_u64 v[8:9], v[12:13], 0, v[8:9]
	s_lshl_b32 s6, s68, 2
	v_lshlrev_b64 v[10:11], 2, v[10:11]
	v_lshl_add_u64 v[8:9], v[8:9], 0, s[6:7]
	v_lshl_add_u64 v[100:101], s[62:63], 0, v[10:11]
	v_lshl_add_u64 v[10:11], s[64:65], 0, v[10:11]
	global_load_dword v99, v[8:9], off
	s_nop 0
	global_load_dword v8, v[8:9], off offset:32
	s_mov_b32 s0, 0xbfb8aa3b
	global_load_dword v10, v[10:11], off
	s_movk_i32 s3, 0x300
	global_load_dword v9, v[100:101], off
	s_waitcnt vmcnt(2)
	v_mul_f32_e32 v8, 0xbfb8aa3b, v8
	v_exp_f32_e32 v8, v8
	s_waitcnt vmcnt(1)
	v_add_f32_e32 v10, v99, v10
	v_max_f32_e32 v99, 0, v10
	v_mul_f32_e64 v10, |v10|, s0
	v_exp_f32_e32 v100, v10
	s_mov_b32 s0, 0x3f2aaaab
	s_waitcnt vmcnt(0)
; #define LAS __attribute__((address_space(3)))
; __device__ __forceinline__ float softplusf(float v) { return fmaxf(v, 0.f) + log1pf(__expf(-fabsf(v))); }
; __device__ NOINL void g1_phase(const LAS Params* lp, int l, LAS unsigned char* lds) {
;     ...
;             const float a = p.ab[(size_t)(row0 + tk) * 16 + dir * 4 + h], bb = p.ab[(size_t)(row0 + tk) * 16 + 8 + dir * 4 + h];
;             float g = -__expf(p.gdn_a_log[l * 8 + dir * 4 + h]) * softplusf(a + p.gdn_dt_bias[l * 8 + dir * 4 + h]);
; #pragma unroll
;             for (int o = 1; o < 64; o <<= 1) { const float t = __shfl_up(g, o); if (lane >= o) g += t; }
;             LAS float* gcs = (LAS float*)(lds + s * SLOT + 17408);
;             const float be = __builtin_amdgcn_rcpf(1.f + __expf(-bb));
;             gcs[dir * 64 + lane] = g; gcs[128 + dir * 64 + lane] = be;
;             float* gb = p.gcbuf + ((((size_t)b * 4 + h) * 36 + c3 * 3 + s) * 2 + dir) * 192;
;             gb[lane] = g; gb[64 + lane] = be; gb[128 + lane] = __expf(g);
	v_mul_f32_e32 v9, 0x3fb8aa3b, v9
	v_exp_f32_e32 v9, v9
	v_add_f32_e32 v101, 1.0, v100
	v_add_f32_e32 v10, -1.0, v101
	v_sub_f32_e32 v11, v10, v101
	v_add_f32_e32 v11, 1.0, v11
	v_sub_f32_e32 v10, v100, v10
	v_add_f32_e32 v102, v10, v11
	v_frexp_mant_f32_e32 v10, v101
	v_cmp_gt_f32_e64 s[56:57], s0, v10
	v_cvt_f64_f32_e32 v[10:11], v101
	v_frexp_exp_i32_f64_e32 v10, v[10:11]
	v_subbrev_co_u32_e64 v10, s[56:57], 0, v10, s[56:57]
	v_sub_u32_e32 v11, 0, v10
	v_ldexp_f32 v101, v101, v11
	v_ldexp_f32 v11, v102, v11
	v_add_f32_e32 v102, -1.0, v101
	v_add_f32_e32 v103, 1.0, v102
	v_sub_f32_e32 v103, v101, v103
	v_add_f32_e32 v103, v11, v103
	v_add_f32_e32 v104, v102, v103
	v_sub_f32_e32 v102, v104, v102
	v_sub_f32_e32 v102, v103, v102
	v_add_f32_e32 v103, 1.0, v101
	v_add_f32_e32 v105, -1.0, v103
	v_sub_f32_e32 v101, v101, v105
	v_add_f32_e32 v11, v11, v101
	v_add_f32_e32 v101, v103, v11
	v_sub_f32_e32 v103, v101, v103
	v_sub_f32_e32 v11, v11, v103
	v_rcp_f32_e32 v103, v101
	v_cvt_f32_i32_e32 v10, v10
	s_mov_b32 s0, 0x3f317218
	v_add_f32_e32 v8, 1.0, v8
	v_mul_f32_e32 v105, v104, v103
	v_mul_f32_e32 v106, v101, v105
	v_fma_f32 v107, v105, v101, -v106
	v_fmac_f32_e32 v107, v105, v11
	v_add_f32_e32 v108, v106, v107
	v_sub_f32_e32 v109, v104, v108
	v_sub_f32_e32 v104, v104, v109
	v_sub_f32_e32 v106, v108, v106
	v_sub_f32_e32 v104, v104, v108
	v_add_f32_e32 v102, v102, v104
	v_sub_f32_e32 v104, v106, v107
	v_add_f32_e32 v102, v104, v102
	v_add_f32_e32 v104, v109, v102
	v_mul_f32_e32 v106, v103, v104
	v_mul_f32_e32 v107, v101, v106
	v_fma_f32 v101, v106, v101, -v107
	v_fmac_f32_e32 v101, v106, v11
	v_sub_f32_e32 v11, v109, v104
	v_add_f32_e32 v11, v102, v11
	v_add_f32_e32 v102, v107, v101
	v_sub_f32_e32 v108, v104, v102
	v_sub_f32_e32 v104, v104, v108
	v_sub_f32_e32 v107, v102, v107
	v_sub_f32_e32 v102, v104, v102
	v_add_f32_e32 v11, v11, v102
	v_sub_f32_e32 v101, v107, v101
	v_add_f32_e32 v11, v101, v11
	v_add_f32_e32 v101, v105, v106
	v_add_f32_e32 v11, v108, v11
	v_sub_f32_e32 v102, v101, v105
	v_mul_f32_e32 v11, v103, v11
	v_sub_f32_e32 v102, v106, v102
	v_add_f32_e32 v11, v102, v11
	v_mul_f32_e32 v105, 0x3f317218, v10
	v_add_f32_e32 v102, v101, v11
	v_fma_f32 v106, v10, s0, -v105
	v_mul_f32_e32 v103, v102, v102
	v_fmac_f32_e32 v106, 0xb102e308, v10
	v_sub_f32_e32 v10, v102, v101
	v_fmamk_f32 v104, v103, 0x3e9b6dac, v215
	v_sub_f32_e32 v10, v11, v10
	v_add_f32_e32 v11, v105, v106
	v_fmaak_f32 v104, v103, v104, 0x3f2aaada
	v_sub_f32_e32 v101, v11, v105
	v_ldexp_f32 v105, v102, 1
	v_mul_f32_e32 v102, v102, v103
	v_mul_f32_e32 v102, v102, v104
	v_add_f32_e32 v103, v105, v102
	v_sub_f32_e32 v104, v103, v105
	v_ldexp_f32 v10, v10, 1
	v_sub_f32_e32 v102, v102, v104
	v_add_f32_e32 v10, v10, v102
	v_add_f32_e32 v102, v103, v10
	v_sub_f32_e32 v103, v102, v103
	v_sub_f32_e32 v10, v10, v103
	v_add_f32_e32 v103, v11, v102
	v_sub_f32_e32 v104, v103, v11
	v_sub_f32_e32 v105, v103, v104
	v_sub_f32_e32 v101, v106, v101
	v_sub_f32_e32 v11, v11, v105
	v_sub_f32_e32 v102, v102, v104
	v_add_f32_e32 v11, v102, v11
	v_add_f32_e32 v102, v101, v10
	v_sub_f32_e32 v104, v102, v101
	v_sub_f32_e32 v105, v102, v104
	v_sub_f32_e32 v101, v101, v105
	v_sub_f32_e32 v10, v10, v104
	v_add_f32_e32 v11, v102, v11
	v_add_f32_e32 v10, v10, v101
	v_add_f32_e32 v101, v103, v11
	v_sub_f32_e32 v102, v101, v103
	v_sub_f32_e32 v11, v11, v102
	v_add_f32_e32 v10, v10, v11
	s_mov_b32 s0, 0x7f800000
	v_add_f32_e32 v10, v101, v10
	v_cmp_neq_f32_e64 s[56:57], s0, v100
	s_mov_b32 s0, 0x33800000
	v_rcp_f32_e32 v8, v8
	v_cndmask_b32_e64 v10, v227, v10, s[56:57]
	v_cmp_ngt_f32_e64 s[56:57], -1.0, v100
	s_nop 1
	v_cndmask_b32_e64 v10, v224, v10, s[56:57]
	v_cmp_neq_f32_e64 s[56:57], -1.0, v100
	s_nop 1
	v_cndmask_b32_e64 v10, v228, v10, s[56:57]
	v_cmp_lt_f32_e64 s[56:57], |v100|, s0
	s_lshl_b32 s0, s67, 2
	s_or_b32 s0, s0, s68
	v_cndmask_b32_e64 v10, v10, v100, s[56:57]
	v_add_f32_e32 v10, v99, v10
	v_add_u32_e32 v99, -1, v203
	v_cmp_lt_i32_e64 s[56:57], v99, v216
	v_mul_f32_e64 v11, v10, -v9
	s_nop 0
	v_cndmask_b32_e64 v99, v99, v203, s[56:57]
	v_lshlrev_b32_e32 v99, 2, v99
	ds_bpermute_b32 v99, v99, v11
	s_waitcnt lgkmcnt(0)
	v_fma_f32 v9, v10, -v9, v99
	v_add_u32_e32 v10, -2, v203
	v_cmp_lt_i32_e64 s[56:57], v10, v216
	v_cndmask_b32_e64 v9, v9, v11, s[54:55]
	s_nop 0
	v_cndmask_b32_e64 v10, v10, v203, s[56:57]
	v_lshlrev_b32_e32 v10, 2, v10
	ds_bpermute_b32 v10, v10, v9
	s_waitcnt lgkmcnt(0)
	v_add_f32_e32 v10, v9, v10
	v_cndmask_b32_e64 v9, v10, v9, s[44:45]
	v_add_u32_e32 v10, -4, v203
	v_cmp_lt_i32_e64 s[56:57], v10, v216
	s_nop 1
	v_cndmask_b32_e64 v10, v10, v203, s[56:57]
	v_lshlrev_b32_e32 v10, 2, v10
	ds_bpermute_b32 v10, v10, v9
	s_waitcnt lgkmcnt(0)
	v_add_f32_e32 v10, v9, v10
	v_cndmask_b32_e64 v9, v10, v9, s[46:47]
	v_add_u32_e32 v10, -8, v203
	v_cmp_lt_i32_e64 s[56:57], v10, v216
	s_nop 1
	v_cndmask_b32_e64 v10, v10, v203, s[56:57]
	v_lshlrev_b32_e32 v10, 2, v10
	ds_bpermute_b32 v10, v10, v9
	s_waitcnt lgkmcnt(0)
	v_add_f32_e32 v10, v9, v10
	v_cndmask_b32_e64 v9, v10, v9, s[48:49]
	v_add_u32_e32 v10, -16, v203
	v_cmp_lt_i32_e64 s[56:57], v10, v216
	s_nop 1
	v_cndmask_b32_e64 v10, v10, v203, s[56:57]
	v_lshlrev_b32_e32 v10, 2, v10
	ds_bpermute_b32 v10, v10, v9
	s_waitcnt lgkmcnt(0)
	v_add_f32_e32 v10, v9, v10
	v_cndmask_b32_e64 v9, v10, v9, s[50:51]
	v_subrev_u32_e32 v10, 32, v203
	v_cmp_lt_i32_e64 s[56:57], v10, v216
	s_nop 1
	v_cndmask_b32_e64 v10, v10, v203, s[56:57]
	v_lshlrev_b32_e32 v10, 2, v10
	ds_bpermute_b32 v10, v10, v9
	s_waitcnt lgkmcnt(0)
	v_add_f32_e32 v10, v9, v10
	v_cndmask_b32_e64 v9, v10, v9, s[52:53]
	v_mad_i64_i32 v[10:11], s[0:1], s0, 36, v[18:19]
	v_lshlrev_b64 v[10:11], 1, v[10:11]
	v_or_b32_e32 v10, v10, v2
	v_mad_u64_u32 v[100:101], s[0:1], v10, s3, v[14:15]
	v_mov_b32_e32 v10, v101
	v_mad_u64_u32 v[10:11], s[0:1], v11, s3, v[10:11]
	v_mov_b32_e32 v101, v10
	ds_write2st64_b32 v26, v9, v8 offset0:68 offset1:70
	global_store_dword v[100:101], v9, off
	global_store_dword v[100:101], v8, off offset:256
	v_mul_f32_e32 v8, 0x3fb8aa3b, v9
	v_exp_f32_e32 v8, v8
	global_store_dword v[100:101], v8, off offset:512

; #define LAS __attribute__((address_space(3)))
; __device__ NOINL void combine_phase(const LAS Params* lp, int l, LAS unsigned char* lds) {
;     ...
;         __syncthreads();
;         {
;             const int ch = tid >> 1, hf = tid & 1;
;             const bf16_t* src = hT + ((size_t)ch * NB + b) * L + t0 + hf * 32;
; #pragma unroll
;             for (int q = 0; q < 4; ++q) {
;                 const u32x4 v = *(const u32x4*)(src + q * 8);
;                 const unsigned uu[4] = {v.x, v.y, v.z, v.w};
; #pragma unroll
;                 for (int e = 0; e < 4; ++e) { const int tk = hf * 32 + q * 8 + 2 * e; ts[tk * 264 + ch] = (bf16_t)(uu[e] & 0xFFFFu); ts[(tk + 1) * 264 + ch] = (bf16_t)(uu[e] >> 16); }
;             }
;         }
;         __syncthreads();
;         {
;             const int tk = tid >> 3, seg = (tid & 7) * 32;
; #pragma unroll
;             for (int q = 0; q < 4; ++q) *(u32x4*)(p.hbuf + (size_t)(row0 + tk) * DM + seg + q * 8) = *(const LAS u32x4*)(ts + tk * 264 + seg + q * 8);
;         }
; #pragma unroll
;         for (int i = 0; i < 8; ++i) {
;             const size_t row = (size_t)(row0 + 8 * w + i);
;             float of[8], ob[8], zz[8];
;             unpack8(*(const u32x4*)(p.hbuf + row * DM + 256 + lane * 8), of); unpack8(*(const u32x4*)(p.hyproj + row * 768 + lane * 8), ob); unpack8(*(const u32x4*)(p.proj + row * 3072 + 1536 + lane * 8), zz);
.LBB0_1396:
	s_ashr_i32 s41, s40, 31
	v_lshl_add_u64 v[16:17], v[2:3], 0, s[40:41]
	v_lshlrev_b64 v[16:17], s52, v[16:17]
	v_lshl_add_u64 v[16:17], v[16:17], 1, s[54:55]
	s_ashr_i32 s51, s50, 31
	v_lshl_add_u64 v[16:17], s[50:51], 1, v[16:17]
	v_lshl_add_u64 v[20:21], v[16:17], 0, v[0:1]
	s_barrier
	global_load_dwordx4 v[70:73], v[20:21], off
	global_load_dwordx4 v[74:77], v[20:21], off offset:16
	global_load_dwordx4 v[78:81], v[20:21], off offset:32
	global_load_dwordx4 v[82:85], v[20:21], off offset:48
	s_add_i32 s29, s29, s88
	s_waitcnt vmcnt(3)
	ds_write_b16 v53, v70
	ds_write_b16_d16_hi v53, v70 offset:528
	ds_write_b16 v53, v71 offset:1056
	ds_write_b16_d16_hi v53, v71 offset:1584
	ds_write_b16 v53, v72 offset:2112
	ds_write_b16_d16_hi v53, v72 offset:2640
	ds_write_b16 v53, v73 offset:3168
	ds_write_b16_d16_hi v53, v73 offset:3696
	s_waitcnt vmcnt(2)
	ds_write_b16 v53, v74 offset:4224
	ds_write_b16_d16_hi v53, v74 offset:4752
	ds_write_b16 v53, v75 offset:5280
	ds_write_b16_d16_hi v53, v75 offset:5808
	ds_write_b16 v53, v76 offset:6336
	ds_write_b16_d16_hi v53, v76 offset:6864
	ds_write_b16 v53, v77 offset:7392
	ds_write_b16_d16_hi v53, v77 offset:7920
	s_waitcnt vmcnt(1)
	ds_write_b16 v53, v78 offset:8448
	ds_write_b16_d16_hi v53, v78 offset:8976
	ds_write_b16 v53, v79 offset:9504
	ds_write_b16_d16_hi v53, v79 offset:10032
	ds_write_b16 v53, v80 offset:10560
	ds_write_b16_d16_hi v53, v80 offset:11088
	ds_write_b16 v53, v81 offset:11616
	ds_write_b16_d16_hi v53, v81 offset:12144
	s_waitcnt vmcnt(0)
	ds_write_b16 v53, v82 offset:12672
	ds_write_b16_d16_hi v53, v82 offset:13200
	ds_write_b16 v53, v83 offset:13728
	ds_write_b16_d16_hi v53, v83 offset:14256
	ds_write_b16 v53, v84 offset:14784
	ds_write_b16_d16_hi v53, v84 offset:15312
	ds_write_b16 v53, v85 offset:15840
	ds_write_b16_d16_hi v53, v85 offset:16368
	v_add_u32_e32 v16, s27, v46
	v_ashrrev_i32_e32 v17, 31, v16
	v_lshlrev_b64 v[16:17], 11, v[16:17]
	s_waitcnt lgkmcnt(0)
	s_barrier
	v_lshl_add_u64 v[56:57], v[24:25], 0, v[16:17]
	ds_read_b128 v[16:19], v47
	ds_read_b128 v[20:23], v47 offset:16
	ds_read_b128 v[38:41], v47 offset:32
	ds_read_b128 v[42:45], v47 offset:48
	s_waitcnt lgkmcnt(3)
	global_store_dwordx4 v[56:57], v[16:19], off
	s_waitcnt lgkmcnt(2)
	global_store_dwordx4 v[56:57], v[20:23], off offset:16
	s_waitcnt lgkmcnt(1)
	global_store_dwordx4 v[56:57], v[38:41], off offset:32
	s_waitcnt lgkmcnt(0)
	global_store_dwordx4 v[56:57], v[42:45], off offset:48
	v_add_u32_e32 v70, s27, v48
	v_ashrrev_i32_e32 v71, 31, v70
	v_lshlrev_b64 v[72:73], 11, v[70:71]
	v_lshl_add_u64 v[74:75], v[28:29], 0, v[72:73]
	v_mad_i64_i32 v[72:73], s[0:1], v70, s84, v[26:27]
	v_mad_i64_i32 v[76:77], s[0:1], v70, s81, v[30:31]
	global_load_dwordx4 v[78:81], v[74:75], off offset:512
	global_load_dwordx4 v[82:85], v[72:73], off
	global_load_dwordx4 v[86:89], v[76:77], off offset:3072
	v_add_u32_e32 v72, 1, v70
	v_ashrrev_i32_e32 v73, 31, v72
	v_mad_i64_i32 v[76:77], s[0:1], v72, s84, v[26:27]
	v_lshlrev_b64 v[90:91], 11, v[72:73]
	v_lshl_add_u64 v[92:93], v[28:29], 0, v[90:91]
	v_mad_i64_i32 v[90:91], s[0:1], v72, s81, v[30:31]
	global_load_dwordx4 v[94:97], v[92:93], off offset:512
	global_load_dwordx4 v[98:101], v[90:91], off offset:3072
	global_load_dwordx4 v[102:105], v[76:77], off
	v_add_u32_e32 v72, 2, v70
	v_ashrrev_i32_e32 v73, 31, v72
	v_mad_i64_i32 v[76:77], s[0:1], v72, s84, v[26:27]
	v_lshlrev_b64 v[90:91], 11, v[72:73]
	v_lshl_add_u64 v[106:107], v[28:29], 0, v[90:91]
	v_mad_i64_i32 v[90:91], s[0:1], v72, s81, v[30:31]
	global_load_dwordx4 v[108:111], v[106:107], off offset:512
	global_load_dwordx4 v[112:115], v[90:91], off offset:3072
	global_load_dwordx4 v[116:119], v[76:77], off
	v_add_u32_e32 v72, 3, v70
	v_ashrrev_i32_e32 v73, 31, v72
	v_mad_i64_i32 v[76:77], s[0:1], v72, s84, v[26:27]
	v_lshlrev_b64 v[90:91], 11, v[72:73]
	v_lshl_add_u64 v[120:121], v[28:29], 0, v[90:91]
	v_mad_i64_i32 v[90:91], s[0:1], v72, s81, v[30:31]
	global_load_dwordx4 v[122:125], v[120:121], off offset:512
	global_load_dwordx4 v[126:129], v[90:91], off offset:3072
	global_load_dwordx4 v[130:133], v[76:77], off
	v_add_u32_e32 v72, 4, v70
	v_ashrrev_i32_e32 v73, 31, v72
	v_mad_i64_i32 v[76:77], s[0:1], v72, s84, v[26:27]
	v_lshlrev_b64 v[90:91], 11, v[72:73]
	v_lshl_add_u64 v[134:135], v[28:29], 0, v[90:91]
	v_mad_i64_i32 v[90:91], s[0:1], v72, s81, v[30:31]
	global_load_dwordx4 v[136:139], v[134:135], off offset:512
	global_load_dwordx4 v[140:143], v[90:91], off offset:3072
	global_load_dwordx4 v[144:147], v[76:77], off
	v_add_u32_e32 v72, 5, v70
	v_ashrrev_i32_e32 v73, 31, v72
	v_mad_i64_i32 v[76:77], s[0:1], v72, s84, v[26:27]
	v_lshlrev_b64 v[90:91], 11, v[72:73]
	v_lshl_add_u64 v[148:149], v[28:29], 0, v[90:91]
	v_mad_i64_i32 v[90:91], s[0:1], v72, s81, v[30:31]
	global_load_dwordx4 v[150:153], v[148:149], off offset:512
	global_load_dwordx4 v[154:157], v[90:91], off offset:3072
	global_load_dwordx4 v[158:161], v[76:77], off
	v_add_u32_e32 v72, 6, v70
	v_ashrrev_i32_e32 v73, 31, v72
	v_mad_i64_i32 v[76:77], s[0:1], v72, s84, v[26:27]
	v_lshlrev_b64 v[90:91], 11, v[72:73]
	v_lshl_add_u64 v[162:163], v[28:29], 0, v[90:91]
	v_mad_i64_i32 v[90:91], s[0:1], v72, s81, v[30:31]
	global_load_dwordx4 v[164:167], v[162:163], off offset:512
	global_load_dwordx4 v[168:171], v[90:91], off offset:3072
	global_load_dwordx4 v[172:175], v[76:77], off
	v_add_u32_e32 v72, 7, v70
	v_ashrrev_i32_e32 v73, 31, v72
	v_lshlrev_b64 v[70:71], 11, v[72:73]
	v_lshl_add_u64 v[76:77], v[28:29], 0, v[70:71]
	v_mad_i64_i32 v[70:71], s[0:1], v72, s84, v[26:27]
	v_mad_i64_i32 v[90:91], s[0:1], v72, s81, v[30:31]
	global_load_dwordx4 v[176:179], v[76:77], off offset:512
	global_load_dwordx4 v[180:183], v[90:91], off offset:3072
	global_load_dwordx4 v[186:189], v[70:71], off
	s_waitcnt vmcnt(23)
; __device__ __forceinline__ unsigned pk2(float lo, float hi) { const f32v2_t f = {lo, hi}; const bf16v2_t b = __builtin_convertvector(f, bf16v2_t); return __builtin_bit_cast(unsigned, b); }
; __device__ __forceinline__ float siluf(float v) { return v * __builtin_amdgcn_rcpf(1.f + __expf(-v)); }
; __device__ NOINL void combine_phase(const LAS Params* lp, int l, LAS unsigned char* lds) {
;     ...
;         for (int i = 0; i < 8; ++i) {
;             const size_t row = (size_t)(row0 + 8 * w + i);
;             float of[8], ob[8], zz[8];
;             unpack8(*(const u32x4*)(p.hbuf + row * DM + 256 + lane * 8), of); unpack8(*(const u32x4*)(p.hyproj + row * 768 + lane * 8), ob); unpack8(*(const u32x4*)(p.proj + row * 3072 + 1536 + lane * 8), zz);
;             float ss = 0.f;
; #pragma unroll
;             for (int e = 0; e < 8; ++e) { of[e] += ob[e]; ss += of[e] * of[e]; }
;             ss += __shfl_xor(ss, 1); ss += __shfl_xor(ss, 2); ss += __shfl_xor(ss, 4); ss += __shfl_xor(ss, 8);
;             const float inv = rsqrtf(ss * (1.f / 128.f) + 1e-6f);
;             float o[8];
; #pragma unroll
;             for (int e = 0; e < 8; ++e) o[e] = of[e] * inv * ng8[e] * siluf(zz[e]);
;             u32x4 pk; pk.x = pk2(o[0], o[1]); pk.y = pk2(o[2], o[3]); pk.z = pk2(o[4], o[5]); pk.w = pk2(o[6], o[7]);
;             *(u32x4*)(p.hbuf + row * DM + 256 + lane * 8) = pk;
	v_lshlrev_b32_e32 v56, 16, v81
	v_and_b32_e32 v57, 0xffff0000, v81
	v_lshlrev_b32_e32 v62, 16, v80
	v_and_b32_e32 v63, 0xffff0000, v80
	s_waitcnt vmcnt(22)
	v_lshlrev_b32_e32 v18, 16, v84
	v_and_b32_e32 v19, 0xffff0000, v84
	s_waitcnt vmcnt(21)
	v_lshlrev_b32_e32 v40, 16, v88
	v_mul_f32_e32 v21, 0xbfb8aa3b, v40
	v_exp_f32_e32 v21, v21
	v_lshlrev_b32_e32 v58, 16, v85
	v_and_b32_e32 v59, 0xffff0000, v85
	v_and_b32_e32 v41, 0xffff0000, v88
	v_add_f32_e32 v21, 1.0, v21
	v_pk_add_f32 v[18:19], v[62:63], v[18:19]
	v_rcp_f32_e32 v62, v21
	v_mul_f32_e32 v21, 0xbfb8aa3b, v41
	v_exp_f32_e32 v21, v21
	v_lshlrev_b32_e32 v66, 16, v87
	v_and_b32_e32 v67, 0xffff0000, v87
	v_lshlrev_b32_e32 v64, 16, v83
	v_add_f32_e32 v21, 1.0, v21
	v_rcp_f32_e32 v63, v21
	v_and_b32_e32 v65, 0xffff0000, v83
	v_and_b32_e32 v39, 0xffff0000, v86
	v_lshlrev_b32_e32 v60, 16, v89
	v_pk_mul_f32 v[40:41], v[62:63], v[40:41]
	v_lshlrev_b32_e32 v62, 16, v79
	v_and_b32_e32 v63, 0xffff0000, v79
	v_mul_f32_e32 v17, 0xbfb8aa3b, v66
	v_exp_f32_e32 v17, v17
	v_pk_add_f32 v[62:63], v[62:63], v[64:65]
	v_and_b32_e32 v61, 0xffff0000, v89
	v_pk_mul_f32 v[64:65], v[62:63], v[62:63]
	v_add_f32_e32 v17, 1.0, v17
	v_rcp_f32_e32 v68, v17
	v_mul_f32_e32 v17, 0xbfb8aa3b, v67
	v_exp_f32_e32 v17, v17
	v_pk_mul_f32 v[44:45], v[18:19], v[18:19]
	v_pk_add_f32 v[56:57], v[56:57], v[58:59]
	v_add_f32_e32 v17, 1.0, v17
	v_rcp_f32_e32 v69, v17
	v_and_b32_e32 v17, 0xffff0000, v82
	v_pk_mul_f32 v[58:59], v[56:57], v[56:57]
	v_pk_mul_f32 v[66:67], v[68:69], v[66:67]
	v_lshlrev_b32_e32 v68, 16, v78
	v_and_b32_e32 v69, 0xffff0000, v78
	v_lshlrev_b32_e32 v16, 16, v82
	v_lshlrev_b32_e32 v38, 16, v86
	v_mul_f32_e32 v21, 0xbfb8aa3b, v38
	v_exp_f32_e32 v21, v21
	v_pk_add_f32 v[16:17], v[68:69], v[16:17]
	v_add_f32_e32 v21, 1.0, v21
	v_rcp_f32_e32 v68, v21
	v_mul_f32_e32 v21, 0xbfb8aa3b, v39
	v_exp_f32_e32 v21, v21
	v_pk_mul_f32 v[42:43], v[16:17], v[16:17]
	v_add_f32_e32 v21, 1.0, v21
	v_rcp_f32_e32 v69, v21
	v_add_f32_e32 v21, v42, v43
	v_add_f32_e32 v21, v64, v21
	v_add_f32_e32 v21, v65, v21
	v_add_f32_e32 v21, v44, v21
	v_add_f32_e32 v21, v45, v21
	v_add_f32_e32 v21, v58, v21
	v_add_f32_e32 v21, v59, v21
	ds_bpermute_b32 v37, v49, v21
	v_pk_mul_f32 v[38:39], v[68:69], v[38:39]
	s_waitcnt lgkmcnt(0)
	v_add_f32_e32 v21, v21, v37
	ds_bpermute_b32 v37, v50, v21
	s_waitcnt lgkmcnt(0)
	v_add_f32_e32 v21, v21, v37
	ds_bpermute_b32 v37, v51, v21
	s_waitcnt lgkmcnt(0)
	v_add_f32_e32 v21, v21, v37
	ds_bpermute_b32 v37, v52, v21
	s_waitcnt lgkmcnt(0)
	v_add_f32_e32 v21, v21, v37
	v_fmamk_f32 v21, v21, 0x3c000000, v211
	v_cmp_gt_f32_e32 vcc, s79, v21
	v_mul_f32_e32 v37, 0x4b800000, v21
	s_nop 0
	v_cndmask_b32_e32 v21, v21, v37, vcc
	v_rsq_f32_e32 v21, v21
	s_nop 0
	v_mul_f32_e32 v37, 0x45800000, v21
	v_cndmask_b32_e32 v42, v21, v37, vcc
	v_mul_f32_e32 v21, 0xbfb8aa3b, v60
	v_exp_f32_e32 v21, v21
	v_pk_mul_f32 v[18:19], v[18:19], v[42:43] op_sel_hi:[1,0]
	v_pk_mul_f32 v[16:17], v[16:17], v[42:43] op_sel_hi:[1,0]
	v_pk_mul_f32 v[18:19], v[8:9], v[18:19]
	v_add_f32_e32 v21, 1.0, v21
	v_pk_mul_f32 v[18:19], v[40:41], v[18:19]
	v_rcp_f32_e32 v40, v21
	v_mul_f32_e32 v21, 0xbfb8aa3b, v61
	v_exp_f32_e32 v21, v21
	v_pk_mul_f32 v[16:17], v[12:13], v[16:17]
	v_cvt_pk_bf16_f32 v18, v18, v19
	v_pk_mul_f32 v[16:17], v[38:39], v[16:17]
	v_add_f32_e32 v21, 1.0, v21
	v_rcp_f32_e32 v41, v21
	v_pk_mul_f32 v[38:39], v[62:63], v[42:43] op_sel_hi:[1,0]
	v_pk_mul_f32 v[42:43], v[56:57], v[42:43] op_sel_hi:[1,0]
	v_pk_mul_f32 v[38:39], v[14:15], v[38:39]
	v_pk_mul_f32 v[42:43], v[10:11], v[42:43]
	v_pk_mul_f32 v[38:39], v[66:67], v[38:39]
	v_pk_mul_f32 v[40:41], v[40:41], v[60:61]
	v_cvt_pk_bf16_f32 v16, v16, v17
	v_pk_mul_f32 v[40:41], v[40:41], v[42:43]
	v_cvt_pk_bf16_f32 v17, v38, v39
	v_cvt_pk_bf16_f32 v19, v40, v41
	global_store_dwordx4 v[74:75], v[16:19], off offset:512
	s_nop 0
	s_waitcnt vmcnt(21)
	v_lshlrev_b32_e32 v38, 16, v97
	v_and_b32_e32 v39, 0xffff0000, v97
	v_lshlrev_b32_e32 v62, 16, v96
	v_and_b32_e32 v63, 0xffff0000, v96
	s_waitcnt vmcnt(20)
	v_lshlrev_b32_e32 v66, 16, v99
	v_and_b32_e32 v67, 0xffff0000, v99
	v_lshlrev_b32_e32 v60, 16, v101
	v_and_b32_e32 v61, 0xffff0000, v101
	s_waitcnt vmcnt(19)
	v_lshlrev_b32_e32 v18, 16, v104
	v_and_b32_e32 v19, 0xffff0000, v104
	v_lshlrev_b32_e32 v42, 16, v100
	v_mul_f32_e32 v21, 0xbfb8aa3b, v42
	v_exp_f32_e32 v21, v21
	v_lshlrev_b32_e32 v44, 16, v105
	v_and_b32_e32 v45, 0xffff0000, v105
	v_and_b32_e32 v43, 0xffff0000, v100
	v_add_f32_e32 v21, 1.0, v21
	v_pk_add_f32 v[18:19], v[62:63], v[18:19]
	v_rcp_f32_e32 v62, v21
	v_mul_f32_e32 v21, 0xbfb8aa3b, v43
	v_exp_f32_e32 v21, v21
	v_lshlrev_b32_e32 v64, 16, v103
	v_and_b32_e32 v65, 0xffff0000, v103
	v_and_b32_e32 v41, 0xffff0000, v98
	v_add_f32_e32 v21, 1.0, v21
	v_rcp_f32_e32 v63, v21
	v_pk_mul_f32 v[58:59], v[18:19], v[18:19]
	v_pk_add_f32 v[38:39], v[38:39], v[44:45]
	v_pk_mul_f32 v[42:43], v[62:63], v[42:43]
	v_lshlrev_b32_e32 v62, 16, v95
	v_and_b32_e32 v63, 0xffff0000, v95
	v_mul_f32_e32 v17, 0xbfb8aa3b, v66
	v_exp_f32_e32 v17, v17
	v_pk_add_f32 v[62:63], v[62:63], v[64:65]
	v_pk_mul_f32 v[44:45], v[38:39], v[38:39]
	v_pk_mul_f32 v[64:65], v[62:63], v[62:63]
	v_add_f32_e32 v17, 1.0, v17
	v_rcp_f32_e32 v68, v17
	v_mul_f32_e32 v17, 0xbfb8aa3b, v67
	v_exp_f32_e32 v17, v17
	s_nop 0
	v_add_f32_e32 v17, 1.0, v17
	v_rcp_f32_e32 v69, v17
	v_and_b32_e32 v17, 0xffff0000, v102
	v_pk_mul_f32 v[66:67], v[68:69], v[66:67]
	v_lshlrev_b32_e32 v68, 16, v94
	v_and_b32_e32 v69, 0xffff0000, v94
	v_lshlrev_b32_e32 v16, 16, v102
	v_lshlrev_b32_e32 v40, 16, v98
	v_mul_f32_e32 v21, 0xbfb8aa3b, v40
	v_exp_f32_e32 v21, v21
	v_pk_add_f32 v[16:17], v[68:69], v[16:17]
	v_add_f32_e32 v21, 1.0, v21
	v_rcp_f32_e32 v68, v21
	v_mul_f32_e32 v21, 0xbfb8aa3b, v41
	v_exp_f32_e32 v21, v21
	v_pk_mul_f32 v[56:57], v[16:17], v[16:17]
	v_add_f32_e32 v21, 1.0, v21
	v_rcp_f32_e32 v69, v21
	v_add_f32_e32 v21, v56, v57
	v_add_f32_e32 v21, v64, v21
	v_add_f32_e32 v21, v65, v21
	v_add_f32_e32 v21, v58, v21
	v_add_f32_e32 v21, v59, v21
	v_add_f32_e32 v21, v44, v21
	v_add_f32_e32 v21, v45, v21
	ds_bpermute_b32 v37, v49, v21
	v_pk_mul_f32 v[40:41], v[68:69], v[40:41]
	s_waitcnt lgkmcnt(0)
; __device__ __forceinline__ unsigned pk2(float lo, float hi) { const f32v2_t f = {lo, hi}; const bf16v2_t b = __builtin_convertvector(f, bf16v2_t); return __builtin_bit_cast(unsigned, b); }
; __device__ __forceinline__ float siluf(float v) { return v * __builtin_amdgcn_rcpf(1.f + __expf(-v)); }
; __device__ NOINL void combine_phase(const LAS Params* lp, int l, LAS unsigned char* lds) {
;     ...
;         for (int i = 0; i < 8; ++i) {
;             const size_t row = (size_t)(row0 + 8 * w + i);
;             float of[8], ob[8], zz[8];
;             unpack8(*(const u32x4*)(p.hbuf + row * DM + 256 + lane * 8), of); unpack8(*(const u32x4*)(p.hyproj + row * 768 + lane * 8), ob); unpack8(*(const u32x4*)(p.proj + row * 3072 + 1536 + lane * 8), zz);
;             float ss = 0.f;
; #pragma unroll
;             for (int e = 0; e < 8; ++e) { of[e] += ob[e]; ss += of[e] * of[e]; }
;             ss += __shfl_xor(ss, 1); ss += __shfl_xor(ss, 2); ss += __shfl_xor(ss, 4); ss += __shfl_xor(ss, 8);
;             const float inv = rsqrtf(ss * (1.f / 128.f) + 1e-6f);
;             float o[8];
; #pragma unroll
;             for (int e = 0; e < 8; ++e) o[e] = of[e] * inv * ng8[e] * siluf(zz[e]);
;             u32x4 pk; pk.x = pk2(o[0], o[1]); pk.y = pk2(o[2], o[3]); pk.z = pk2(o[4], o[5]); pk.w = pk2(o[6], o[7]);
;             *(u32x4*)(p.hbuf + row * DM + 256 + lane * 8) = pk;
	v_add_f32_e32 v21, v21, v37
	ds_bpermute_b32 v37, v50, v21
	s_waitcnt lgkmcnt(0)
	v_add_f32_e32 v21, v21, v37
	ds_bpermute_b32 v37, v51, v21
	s_waitcnt lgkmcnt(0)
	v_add_f32_e32 v21, v21, v37
	ds_bpermute_b32 v37, v52, v21
	s_waitcnt lgkmcnt(0)
	v_add_f32_e32 v21, v21, v37
	v_fmamk_f32 v21, v21, 0x3c000000, v211
	v_cmp_gt_f32_e32 vcc, s79, v21
	v_mul_f32_e32 v37, 0x4b800000, v21
	s_nop 0
	v_cndmask_b32_e32 v21, v21, v37, vcc
	v_rsq_f32_e32 v21, v21
	s_nop 0
	v_mul_f32_e32 v37, 0x45800000, v21
	v_cndmask_b32_e32 v44, v21, v37, vcc
	v_mul_f32_e32 v21, 0xbfb8aa3b, v60
	v_exp_f32_e32 v21, v21
	v_pk_mul_f32 v[18:19], v[18:19], v[44:45] op_sel_hi:[1,0]
	v_pk_mul_f32 v[16:17], v[16:17], v[44:45] op_sel_hi:[1,0]
	v_pk_mul_f32 v[18:19], v[8:9], v[18:19]
	v_add_f32_e32 v21, 1.0, v21
	v_pk_mul_f32 v[18:19], v[42:43], v[18:19]
	v_rcp_f32_e32 v42, v21
	v_mul_f32_e32 v21, 0xbfb8aa3b, v61
	v_exp_f32_e32 v21, v21
	v_pk_mul_f32 v[16:17], v[12:13], v[16:17]
	v_pk_mul_f32 v[38:39], v[38:39], v[44:45] op_sel_hi:[1,0]
	v_pk_mul_f32 v[16:17], v[40:41], v[16:17]
	v_add_f32_e32 v21, 1.0, v21
	v_rcp_f32_e32 v43, v21
	v_pk_mul_f32 v[40:41], v[62:63], v[44:45] op_sel_hi:[1,0]
	v_pk_mul_f32 v[38:39], v[10:11], v[38:39]
	v_pk_mul_f32 v[40:41], v[14:15], v[40:41]
	v_pk_mul_f32 v[42:43], v[42:43], v[60:61]
	v_pk_mul_f32 v[40:41], v[66:67], v[40:41]
	v_pk_mul_f32 v[38:39], v[42:43], v[38:39]
	v_cvt_pk_bf16_f32 v18, v18, v19
	v_cvt_pk_bf16_f32 v19, v38, v39
	v_cvt_pk_bf16_f32 v16, v16, v17
	v_cvt_pk_bf16_f32 v17, v40, v41
	global_store_dwordx4 v[92:93], v[16:19], off offset:512
	s_nop 0
	s_waitcnt vmcnt(19)
	v_lshlrev_b32_e32 v38, 16, v111
	v_and_b32_e32 v39, 0xffff0000, v111
	v_lshlrev_b32_e32 v62, 16, v110
	v_and_b32_e32 v63, 0xffff0000, v110
	s_waitcnt vmcnt(18)
	v_lshlrev_b32_e32 v66, 16, v113
	v_and_b32_e32 v67, 0xffff0000, v113
	v_lshlrev_b32_e32 v60, 16, v115
	v_and_b32_e32 v61, 0xffff0000, v115
	s_waitcnt vmcnt(17)
	v_lshlrev_b32_e32 v18, 16, v118
	v_and_b32_e32 v19, 0xffff0000, v118
	v_lshlrev_b32_e32 v42, 16, v114
	v_mul_f32_e32 v21, 0xbfb8aa3b, v42
	v_exp_f32_e32 v21, v21
	v_lshlrev_b32_e32 v44, 16, v119
	v_and_b32_e32 v45, 0xffff0000, v119
	v_and_b32_e32 v43, 0xffff0000, v114
	v_add_f32_e32 v21, 1.0, v21
	v_pk_add_f32 v[18:19], v[62:63], v[18:19]
	v_rcp_f32_e32 v62, v21
	v_mul_f32_e32 v21, 0xbfb8aa3b, v43
	v_exp_f32_e32 v21, v21
	v_lshlrev_b32_e32 v64, 16, v117
	v_and_b32_e32 v65, 0xffff0000, v117
	v_and_b32_e32 v41, 0xffff0000, v112
	v_add_f32_e32 v21, 1.0, v21
	v_rcp_f32_e32 v63, v21
	v_pk_mul_f32 v[58:59], v[18:19], v[18:19]
	v_pk_add_f32 v[38:39], v[38:39], v[44:45]
	v_pk_mul_f32 v[42:43], v[62:63], v[42:43]
	v_lshlrev_b32_e32 v62, 16, v109
	v_and_b32_e32 v63, 0xffff0000, v109
	v_mul_f32_e32 v17, 0xbfb8aa3b, v66
	v_exp_f32_e32 v17, v17
	v_pk_add_f32 v[62:63], v[62:63], v[64:65]
	v_pk_mul_f32 v[44:45], v[38:39], v[38:39]
	v_pk_mul_f32 v[64:65], v[62:63], v[62:63]
	v_add_f32_e32 v17, 1.0, v17
	v_rcp_f32_e32 v68, v17
	v_mul_f32_e32 v17, 0xbfb8aa3b, v67
	v_exp_f32_e32 v17, v17
	s_nop 0
	v_add_f32_e32 v17, 1.0, v17
	v_rcp_f32_e32 v69, v17
	v_and_b32_e32 v17, 0xffff0000, v116
	v_pk_mul_f32 v[66:67], v[68:69], v[66:67]
	v_lshlrev_b32_e32 v68, 16, v108
	v_and_b32_e32 v69, 0xffff0000, v108
	v_lshlrev_b32_e32 v16, 16, v116
	v_lshlrev_b32_e32 v40, 16, v112
	v_mul_f32_e32 v21, 0xbfb8aa3b, v40
	v_exp_f32_e32 v21, v21
	v_pk_add_f32 v[16:17], v[68:69], v[16:17]
	v_add_f32_e32 v21, 1.0, v21
	v_rcp_f32_e32 v68, v21
	v_mul_f32_e32 v21, 0xbfb8aa3b, v41
	v_exp_f32_e32 v21, v21
	v_pk_mul_f32 v[56:57], v[16:17], v[16:17]
	v_add_f32_e32 v21, 1.0, v21
	v_rcp_f32_e32 v69, v21
	v_add_f32_e32 v21, v56, v57
	v_add_f32_e32 v21, v64, v21
	v_add_f32_e32 v21, v65, v21
	v_add_f32_e32 v21, v58, v21
	v_add_f32_e32 v21, v59, v21
	v_add_f32_e32 v21, v44, v21
	v_add_f32_e32 v21, v45, v21
	ds_bpermute_b32 v37, v49, v21
	v_pk_mul_f32 v[40:41], v[68:69], v[40:41]
	s_waitcnt lgkmcnt(0)
	v_add_f32_e32 v21, v21, v37
	ds_bpermute_b32 v37, v50, v21
	s_waitcnt lgkmcnt(0)
	v_add_f32_e32 v21, v21, v37
	ds_bpermute_b32 v37, v51, v21
	s_waitcnt lgkmcnt(0)
	v_add_f32_e32 v21, v21, v37
	ds_bpermute_b32 v37, v52, v21
	s_waitcnt lgkmcnt(0)
	v_add_f32_e32 v21, v21, v37
	v_fmamk_f32 v21, v21, 0x3c000000, v211
	v_cmp_gt_f32_e32 vcc, s79, v21
	v_mul_f32_e32 v37, 0x4b800000, v21
	s_nop 0
	v_cndmask_b32_e32 v21, v21, v37, vcc
	v_rsq_f32_e32 v21, v21
	s_nop 0
	v_mul_f32_e32 v37, 0x45800000, v21
	v_cndmask_b32_e32 v44, v21, v37, vcc
	v_mul_f32_e32 v21, 0xbfb8aa3b, v60
	v_exp_f32_e32 v21, v21
	v_pk_mul_f32 v[18:19], v[18:19], v[44:45] op_sel_hi:[1,0]
	v_pk_mul_f32 v[16:17], v[16:17], v[44:45] op_sel_hi:[1,0]
	v_pk_mul_f32 v[18:19], v[8:9], v[18:19]
	v_add_f32_e32 v21, 1.0, v21
	v_pk_mul_f32 v[18:19], v[42:43], v[18:19]
	v_rcp_f32_e32 v42, v21
	v_mul_f32_e32 v21, 0xbfb8aa3b, v61
	v_exp_f32_e32 v21, v21
	v_pk_mul_f32 v[16:17], v[12:13], v[16:17]
	v_pk_mul_f32 v[38:39], v[38:39], v[44:45] op_sel_hi:[1,0]
	v_pk_mul_f32 v[16:17], v[40:41], v[16:17]
	v_add_f32_e32 v21, 1.0, v21
	v_rcp_f32_e32 v43, v21
	v_pk_mul_f32 v[40:41], v[62:63], v[44:45] op_sel_hi:[1,0]
	v_pk_mul_f32 v[38:39], v[10:11], v[38:39]
	v_pk_mul_f32 v[40:41], v[14:15], v[40:41]
	v_pk_mul_f32 v[42:43], v[42:43], v[60:61]
	v_pk_mul_f32 v[40:41], v[66:67], v[40:41]
	v_pk_mul_f32 v[38:39], v[42:43], v[38:39]
	v_cvt_pk_bf16_f32 v18, v18, v19
	v_cvt_pk_bf16_f32 v19, v38, v39
	v_cvt_pk_bf16_f32 v16, v16, v17
	v_cvt_pk_bf16_f32 v17, v40, v41
	global_store_dwordx4 v[106:107], v[16:19], off offset:512
	s_nop 0
	s_waitcnt vmcnt(17)
	v_lshlrev_b32_e32 v38, 16, v125
	v_and_b32_e32 v39, 0xffff0000, v125
	v_lshlrev_b32_e32 v62, 16, v124
	v_and_b32_e32 v63, 0xffff0000, v124
	s_waitcnt vmcnt(16)
; __device__ __forceinline__ unsigned pk2(float lo, float hi) { const f32v2_t f = {lo, hi}; const bf16v2_t b = __builtin_convertvector(f, bf16v2_t); return __builtin_bit_cast(unsigned, b); }
; __device__ __forceinline__ float siluf(float v) { return v * __builtin_amdgcn_rcpf(1.f + __expf(-v)); }
; __device__ NOINL void combine_phase(const LAS Params* lp, int l, LAS unsigned char* lds) {
;     ...
;         for (int i = 0; i < 8; ++i) {
;             const size_t row = (size_t)(row0 + 8 * w + i);
;             float of[8], ob[8], zz[8];
;             unpack8(*(const u32x4*)(p.hbuf + row * DM + 256 + lane * 8), of); unpack8(*(const u32x4*)(p.hyproj + row * 768 + lane * 8), ob); unpack8(*(const u32x4*)(p.proj + row * 3072 + 1536 + lane * 8), zz);
;             float ss = 0.f;
; #pragma unroll
;             for (int e = 0; e < 8; ++e) { of[e] += ob[e]; ss += of[e] * of[e]; }
;             ss += __shfl_xor(ss, 1); ss += __shfl_xor(ss, 2); ss += __shfl_xor(ss, 4); ss += __shfl_xor(ss, 8);
;             const float inv = rsqrtf(ss * (1.f / 128.f) + 1e-6f);
;             float o[8];
; #pragma unroll
;             for (int e = 0; e < 8; ++e) o[e] = of[e] * inv * ng8[e] * siluf(zz[e]);
;             u32x4 pk; pk.x = pk2(o[0], o[1]); pk.y = pk2(o[2], o[3]); pk.z = pk2(o[4], o[5]); pk.w = pk2(o[6], o[7]);
;             *(u32x4*)(p.hbuf + row * DM + 256 + lane * 8) = pk;
;         }
; #pragma unroll
;         for (int i = 0; i < 4; ++i) {
;             const size_t row = (size_t)(row0 + 8 * w + 2 * i + (lane >> 5)); const int l32 = lane & 31;
;             float of[8], ob[8], gg[8];
;             unpack8(*(const u32x4*)(p.hbuf + row * DM + 768 + l32 * 8), of); unpack8(*(const u32x4*)(p.hyproj + row * 768 + 512 + l32 * 8), ob); unpack8(*(const u32x4*)(p.proj + row * 3072 + 2816 + l32 * 8), gg);
	v_lshlrev_b32_e32 v66, 16, v127
	v_and_b32_e32 v67, 0xffff0000, v127
	v_lshlrev_b32_e32 v60, 16, v129
	v_and_b32_e32 v61, 0xffff0000, v129
	s_waitcnt vmcnt(15)
	v_lshlrev_b32_e32 v18, 16, v132
	v_and_b32_e32 v19, 0xffff0000, v132
	v_lshlrev_b32_e32 v42, 16, v128
	v_mul_f32_e32 v21, 0xbfb8aa3b, v42
	v_exp_f32_e32 v21, v21
	v_lshlrev_b32_e32 v44, 16, v133
	v_and_b32_e32 v45, 0xffff0000, v133
	v_and_b32_e32 v43, 0xffff0000, v128
	v_add_f32_e32 v21, 1.0, v21
	v_pk_add_f32 v[18:19], v[62:63], v[18:19]
	v_rcp_f32_e32 v62, v21
	v_mul_f32_e32 v21, 0xbfb8aa3b, v43
	v_exp_f32_e32 v21, v21
	v_lshlrev_b32_e32 v64, 16, v131
	v_and_b32_e32 v65, 0xffff0000, v131
	v_and_b32_e32 v41, 0xffff0000, v126
	v_add_f32_e32 v21, 1.0, v21
	v_rcp_f32_e32 v63, v21
	v_pk_mul_f32 v[58:59], v[18:19], v[18:19]
	v_pk_add_f32 v[38:39], v[38:39], v[44:45]
	v_pk_mul_f32 v[42:43], v[62:63], v[42:43]
	v_lshlrev_b32_e32 v62, 16, v123
	v_and_b32_e32 v63, 0xffff0000, v123
	v_mul_f32_e32 v17, 0xbfb8aa3b, v66
	v_exp_f32_e32 v17, v17
	v_pk_add_f32 v[62:63], v[62:63], v[64:65]
	v_pk_mul_f32 v[44:45], v[38:39], v[38:39]
	v_pk_mul_f32 v[64:65], v[62:63], v[62:63]
	v_add_f32_e32 v17, 1.0, v17
	v_rcp_f32_e32 v68, v17
	v_mul_f32_e32 v17, 0xbfb8aa3b, v67
	v_exp_f32_e32 v17, v17
	s_nop 0
	v_add_f32_e32 v17, 1.0, v17
	v_rcp_f32_e32 v69, v17
	v_and_b32_e32 v17, 0xffff0000, v130
	v_pk_mul_f32 v[66:67], v[68:69], v[66:67]
	v_lshlrev_b32_e32 v68, 16, v122
	v_and_b32_e32 v69, 0xffff0000, v122
	v_lshlrev_b32_e32 v16, 16, v130
	v_lshlrev_b32_e32 v40, 16, v126
	v_mul_f32_e32 v21, 0xbfb8aa3b, v40
	v_exp_f32_e32 v21, v21
	v_pk_add_f32 v[16:17], v[68:69], v[16:17]
	v_add_f32_e32 v21, 1.0, v21
	v_rcp_f32_e32 v68, v21
	v_mul_f32_e32 v21, 0xbfb8aa3b, v41
	v_exp_f32_e32 v21, v21
	v_pk_mul_f32 v[56:57], v[16:17], v[16:17]
	v_add_f32_e32 v21, 1.0, v21
	v_rcp_f32_e32 v69, v21
	v_add_f32_e32 v21, v56, v57
	v_add_f32_e32 v21, v64, v21
	v_add_f32_e32 v21, v65, v21
	v_add_f32_e32 v21, v58, v21
	v_add_f32_e32 v21, v59, v21
	v_add_f32_e32 v21, v44, v21
	v_add_f32_e32 v21, v45, v21
	ds_bpermute_b32 v37, v49, v21
	v_pk_mul_f32 v[40:41], v[68:69], v[40:41]
	s_waitcnt lgkmcnt(0)
	v_add_f32_e32 v21, v21, v37
	ds_bpermute_b32 v37, v50, v21
	s_waitcnt lgkmcnt(0)
	v_add_f32_e32 v21, v21, v37
	ds_bpermute_b32 v37, v51, v21
	s_waitcnt lgkmcnt(0)
	v_add_f32_e32 v21, v21, v37
	ds_bpermute_b32 v37, v52, v21
	s_waitcnt lgkmcnt(0)
	v_add_f32_e32 v21, v21, v37
	v_fmamk_f32 v21, v21, 0x3c000000, v211
	v_cmp_gt_f32_e32 vcc, s79, v21
	v_mul_f32_e32 v37, 0x4b800000, v21
	s_nop 0
	v_cndmask_b32_e32 v21, v21, v37, vcc
	v_rsq_f32_e32 v21, v21
	s_nop 0
	v_mul_f32_e32 v37, 0x45800000, v21
	v_cndmask_b32_e32 v44, v21, v37, vcc
	v_mul_f32_e32 v21, 0xbfb8aa3b, v60
	v_exp_f32_e32 v21, v21
	v_pk_mul_f32 v[18:19], v[18:19], v[44:45] op_sel_hi:[1,0]
	v_pk_mul_f32 v[16:17], v[16:17], v[44:45] op_sel_hi:[1,0]
	v_pk_mul_f32 v[18:19], v[8:9], v[18:19]
	v_add_f32_e32 v21, 1.0, v21
	v_pk_mul_f32 v[18:19], v[42:43], v[18:19]
	v_rcp_f32_e32 v42, v21
	v_mul_f32_e32 v21, 0xbfb8aa3b, v61
	v_exp_f32_e32 v21, v21
	v_pk_mul_f32 v[16:17], v[12:13], v[16:17]
	v_pk_mul_f32 v[38:39], v[38:39], v[44:45] op_sel_hi:[1,0]
	v_pk_mul_f32 v[16:17], v[40:41], v[16:17]
	v_add_f32_e32 v21, 1.0, v21
	v_rcp_f32_e32 v43, v21
	v_pk_mul_f32 v[40:41], v[62:63], v[44:45] op_sel_hi:[1,0]
	v_pk_mul_f32 v[38:39], v[10:11], v[38:39]
	v_pk_mul_f32 v[40:41], v[14:15], v[40:41]
	v_pk_mul_f32 v[42:43], v[42:43], v[60:61]
	v_pk_mul_f32 v[40:41], v[66:67], v[40:41]
	v_pk_mul_f32 v[38:39], v[42:43], v[38:39]
	v_cvt_pk_bf16_f32 v18, v18, v19
	v_cvt_pk_bf16_f32 v19, v38, v39
	v_cvt_pk_bf16_f32 v16, v16, v17
	v_cvt_pk_bf16_f32 v17, v40, v41
	global_store_dwordx4 v[120:121], v[16:19], off offset:512
	v_add_u32_e32 v70, s27, v54
	v_mov_b64_e32 v[72:73], s[44:45]
	v_ashrrev_i32_e32 v71, 31, v70
	v_mad_i64_i32 v[74:75], s[0:1], v70, s81, v[72:73]
	v_mov_b32_e32 v79, v1
	v_mov_b32_e32 v78, v36
	v_lshl_add_u64 v[80:81], v[74:75], 0, v[78:79]
	v_mad_i64_i32 v[74:75], s[0:1], v70, s84, v[34:35]
	v_lshlrev_b64 v[82:83], 11, v[70:71]
	v_lshl_add_u64 v[84:85], v[32:33], 0, v[82:83]
	v_add_co_u32_e32 v82, vcc, s83, v80
	global_load_dwordx4 v[86:89], v[84:85], off offset:1536
	s_nop 0
	v_addc_co_u32_e32 v83, vcc, 0, v81, vcc
	global_load_dwordx4 v[90:93], v[74:75], off offset:1024
	global_load_dwordx4 v[94:97], v[82:83], off offset:1536
	v_add_u32_e32 v74, 2, v70
	v_ashrrev_i32_e32 v75, 31, v74
	v_mad_i64_i32 v[80:81], s[0:1], v74, s84, v[34:35]
	v_lshlrev_b64 v[82:83], 11, v[74:75]
	v_mad_i64_i32 v[98:99], s[0:1], v74, s81, v[72:73]
	v_lshl_add_u64 v[74:75], v[98:99], 0, v[78:79]
	v_lshl_add_u64 v[98:99], v[32:33], 0, v[82:83]
	v_add_co_u32_e32 v82, vcc, s83, v74
	global_load_dwordx4 v[100:103], v[98:99], off offset:1536
	s_nop 0
	v_addc_co_u32_e32 v83, vcc, 0, v75, vcc
	global_load_dwordx4 v[104:107], v[80:81], off offset:1024
	global_load_dwordx4 v[108:111], v[82:83], off offset:1536
	v_add_u32_e32 v74, 4, v70
	v_ashrrev_i32_e32 v75, 31, v74
	v_mad_i64_i32 v[80:81], s[0:1], v74, s84, v[34:35]
	v_lshlrev_b64 v[82:83], 11, v[74:75]
	v_mad_i64_i32 v[112:113], s[0:1], v74, s81, v[72:73]
	v_lshl_add_u64 v[74:75], v[112:113], 0, v[78:79]
	v_lshl_add_u64 v[112:113], v[32:33], 0, v[82:83]
	v_add_co_u32_e32 v82, vcc, s83, v74
	global_load_dwordx4 v[114:117], v[112:113], off offset:1536
	s_nop 0
	v_addc_co_u32_e32 v83, vcc, 0, v75, vcc
	global_load_dwordx4 v[118:121], v[80:81], off offset:1024
	global_load_dwordx4 v[122:125], v[82:83], off offset:1536
	v_add_u32_e32 v74, 6, v70
	v_ashrrev_i32_e32 v75, 31, v74
	v_mad_i64_i32 v[70:71], s[0:1], v74, s81, v[72:73]
	v_lshlrev_b64 v[72:73], 11, v[74:75]
	v_lshl_add_u64 v[80:81], v[70:71], 0, v[78:79]
	v_lshl_add_u64 v[70:71], v[32:33], 0, v[72:73]
	v_mad_i64_i32 v[72:73], s[0:1], v74, s84, v[34:35]
	v_add_co_u32_e32 v74, vcc, s83, v80
	global_load_dwordx4 v[126:129], v[70:71], off offset:1536
	s_nop 0
	v_addc_co_u32_e32 v75, vcc, 0, v81, vcc
	global_load_dwordx4 v[78:81], v[72:73], off offset:1024
	global_load_dwordx4 v[130:133], v[74:75], off offset:1536
	s_nop 0
	s_waitcnt vmcnt(27)
; __device__ __forceinline__ unsigned pk2(float lo, float hi) { const f32v2_t f = {lo, hi}; const bf16v2_t b = __builtin_convertvector(f, bf16v2_t); return __builtin_bit_cast(unsigned, b); }
; __device__ __forceinline__ float siluf(float v) { return v * __builtin_amdgcn_rcpf(1.f + __expf(-v)); }
; __device__ NOINL void combine_phase(const LAS Params* lp, int l, LAS unsigned char* lds) {
;     ...
;         for (int i = 0; i < 8; ++i) {
;             const size_t row = (size_t)(row0 + 8 * w + i);
;             float of[8], ob[8], zz[8];
;             unpack8(*(const u32x4*)(p.hbuf + row * DM + 256 + lane * 8), of); unpack8(*(const u32x4*)(p.hyproj + row * 768 + lane * 8), ob); unpack8(*(const u32x4*)(p.proj + row * 3072 + 1536 + lane * 8), zz);
;             float ss = 0.f;
; #pragma unroll
;             for (int e = 0; e < 8; ++e) { of[e] += ob[e]; ss += of[e] * of[e]; }
;             ss += __shfl_xor(ss, 1); ss += __shfl_xor(ss, 2); ss += __shfl_xor(ss, 4); ss += __shfl_xor(ss, 8);
;             const float inv = rsqrtf(ss * (1.f / 128.f) + 1e-6f);
;             float o[8];
; #pragma unroll
;             for (int e = 0; e < 8; ++e) o[e] = of[e] * inv * ng8[e] * siluf(zz[e]);
;             u32x4 pk; pk.x = pk2(o[0], o[1]); pk.y = pk2(o[2], o[3]); pk.z = pk2(o[4], o[5]); pk.w = pk2(o[6], o[7]);
;             *(u32x4*)(p.hbuf + row * DM + 256 + lane * 8) = pk;
	v_lshlrev_b32_e32 v38, 16, v139
	v_and_b32_e32 v39, 0xffff0000, v139
	v_lshlrev_b32_e32 v62, 16, v138
	v_and_b32_e32 v63, 0xffff0000, v138
	s_waitcnt vmcnt(26)
	v_lshlrev_b32_e32 v66, 16, v141
	v_and_b32_e32 v67, 0xffff0000, v141
	v_lshlrev_b32_e32 v60, 16, v143
	v_and_b32_e32 v61, 0xffff0000, v143
	s_waitcnt vmcnt(25)
	v_lshlrev_b32_e32 v18, 16, v146
	v_and_b32_e32 v19, 0xffff0000, v146
	v_lshlrev_b32_e32 v42, 16, v142
	v_mul_f32_e32 v21, 0xbfb8aa3b, v42
	v_exp_f32_e32 v21, v21
	v_lshlrev_b32_e32 v44, 16, v147
	v_and_b32_e32 v45, 0xffff0000, v147
	v_and_b32_e32 v43, 0xffff0000, v142
	v_add_f32_e32 v21, 1.0, v21
	v_pk_add_f32 v[18:19], v[62:63], v[18:19]
	v_rcp_f32_e32 v62, v21
	v_mul_f32_e32 v21, 0xbfb8aa3b, v43
	v_exp_f32_e32 v21, v21
	v_lshlrev_b32_e32 v64, 16, v145
	v_and_b32_e32 v65, 0xffff0000, v145
	v_and_b32_e32 v41, 0xffff0000, v140
	v_add_f32_e32 v21, 1.0, v21
	v_rcp_f32_e32 v63, v21
	v_pk_mul_f32 v[58:59], v[18:19], v[18:19]
	v_pk_add_f32 v[38:39], v[38:39], v[44:45]
	v_pk_mul_f32 v[42:43], v[62:63], v[42:43]
	v_lshlrev_b32_e32 v62, 16, v137
	v_and_b32_e32 v63, 0xffff0000, v137
	v_mul_f32_e32 v17, 0xbfb8aa3b, v66
	v_exp_f32_e32 v17, v17
	v_pk_add_f32 v[62:63], v[62:63], v[64:65]
	v_pk_mul_f32 v[44:45], v[38:39], v[38:39]
	v_pk_mul_f32 v[64:65], v[62:63], v[62:63]
	v_add_f32_e32 v17, 1.0, v17
	v_rcp_f32_e32 v68, v17
	v_mul_f32_e32 v17, 0xbfb8aa3b, v67
	v_exp_f32_e32 v17, v17
	s_nop 0
	v_add_f32_e32 v17, 1.0, v17
	v_rcp_f32_e32 v69, v17
	v_and_b32_e32 v17, 0xffff0000, v144
	v_pk_mul_f32 v[66:67], v[68:69], v[66:67]
	v_lshlrev_b32_e32 v68, 16, v136
	v_and_b32_e32 v69, 0xffff0000, v136
	v_lshlrev_b32_e32 v16, 16, v144
	v_lshlrev_b32_e32 v40, 16, v140
	v_mul_f32_e32 v21, 0xbfb8aa3b, v40
	v_exp_f32_e32 v21, v21
	v_pk_add_f32 v[16:17], v[68:69], v[16:17]
	v_add_f32_e32 v21, 1.0, v21
	v_rcp_f32_e32 v68, v21
	v_mul_f32_e32 v21, 0xbfb8aa3b, v41
	v_exp_f32_e32 v21, v21
	v_pk_mul_f32 v[56:57], v[16:17], v[16:17]
	v_add_f32_e32 v21, 1.0, v21
	v_rcp_f32_e32 v69, v21
	v_add_f32_e32 v21, v56, v57
	v_add_f32_e32 v21, v64, v21
	v_add_f32_e32 v21, v65, v21
	v_add_f32_e32 v21, v58, v21
	v_add_f32_e32 v21, v59, v21
	v_add_f32_e32 v21, v44, v21
	v_add_f32_e32 v21, v45, v21
	ds_bpermute_b32 v37, v49, v21
	v_pk_mul_f32 v[40:41], v[68:69], v[40:41]
	s_waitcnt lgkmcnt(0)
	v_add_f32_e32 v21, v21, v37
	ds_bpermute_b32 v37, v50, v21
	s_waitcnt lgkmcnt(0)
	v_add_f32_e32 v21, v21, v37
	ds_bpermute_b32 v37, v51, v21
	s_waitcnt lgkmcnt(0)
	v_add_f32_e32 v21, v21, v37
	ds_bpermute_b32 v37, v52, v21
	s_waitcnt lgkmcnt(0)
	v_add_f32_e32 v21, v21, v37
	v_fmamk_f32 v21, v21, 0x3c000000, v211
	v_cmp_gt_f32_e32 vcc, s79, v21
	v_mul_f32_e32 v37, 0x4b800000, v21
	s_nop 0
	v_cndmask_b32_e32 v21, v21, v37, vcc
	v_rsq_f32_e32 v21, v21
	s_nop 0
	v_mul_f32_e32 v37, 0x45800000, v21
	v_cndmask_b32_e32 v44, v21, v37, vcc
	v_mul_f32_e32 v21, 0xbfb8aa3b, v60
	v_exp_f32_e32 v21, v21
	v_pk_mul_f32 v[18:19], v[18:19], v[44:45] op_sel_hi:[1,0]
	v_pk_mul_f32 v[16:17], v[16:17], v[44:45] op_sel_hi:[1,0]
	v_pk_mul_f32 v[18:19], v[8:9], v[18:19]
	v_add_f32_e32 v21, 1.0, v21
	v_pk_mul_f32 v[18:19], v[42:43], v[18:19]
	v_rcp_f32_e32 v42, v21
	v_mul_f32_e32 v21, 0xbfb8aa3b, v61
	v_exp_f32_e32 v21, v21
	v_pk_mul_f32 v[16:17], v[12:13], v[16:17]
	v_pk_mul_f32 v[38:39], v[38:39], v[44:45] op_sel_hi:[1,0]
	v_pk_mul_f32 v[16:17], v[40:41], v[16:17]
	v_add_f32_e32 v21, 1.0, v21
	v_rcp_f32_e32 v43, v21
	v_pk_mul_f32 v[40:41], v[62:63], v[44:45] op_sel_hi:[1,0]
	v_pk_mul_f32 v[38:39], v[10:11], v[38:39]
	v_pk_mul_f32 v[40:41], v[14:15], v[40:41]
	v_pk_mul_f32 v[42:43], v[42:43], v[60:61]
	v_pk_mul_f32 v[40:41], v[66:67], v[40:41]
	v_pk_mul_f32 v[38:39], v[42:43], v[38:39]
	v_cvt_pk_bf16_f32 v18, v18, v19
	v_cvt_pk_bf16_f32 v19, v38, v39
	v_cvt_pk_bf16_f32 v16, v16, v17
	v_cvt_pk_bf16_f32 v17, v40, v41
	global_store_dwordx4 v[134:135], v[16:19], off offset:512
	s_nop 0
	s_waitcnt vmcnt(25)
	v_lshlrev_b32_e32 v38, 16, v153
	v_and_b32_e32 v39, 0xffff0000, v153
	v_lshlrev_b32_e32 v62, 16, v152
	v_and_b32_e32 v63, 0xffff0000, v152
	s_waitcnt vmcnt(24)
	v_lshlrev_b32_e32 v66, 16, v155
	v_and_b32_e32 v67, 0xffff0000, v155
	v_lshlrev_b32_e32 v60, 16, v157
	v_and_b32_e32 v61, 0xffff0000, v157
	s_waitcnt vmcnt(23)
	v_lshlrev_b32_e32 v18, 16, v160
	v_and_b32_e32 v19, 0xffff0000, v160
	v_lshlrev_b32_e32 v42, 16, v156
	v_mul_f32_e32 v21, 0xbfb8aa3b, v42
	v_exp_f32_e32 v21, v21
	v_lshlrev_b32_e32 v44, 16, v161
	v_and_b32_e32 v45, 0xffff0000, v161
	v_and_b32_e32 v43, 0xffff0000, v156
	v_add_f32_e32 v21, 1.0, v21
	v_pk_add_f32 v[18:19], v[62:63], v[18:19]
	v_rcp_f32_e32 v62, v21
	v_mul_f32_e32 v21, 0xbfb8aa3b, v43
	v_exp_f32_e32 v21, v21
	v_lshlrev_b32_e32 v64, 16, v159
	v_and_b32_e32 v65, 0xffff0000, v159
	v_and_b32_e32 v41, 0xffff0000, v154
	v_add_f32_e32 v21, 1.0, v21
	v_rcp_f32_e32 v63, v21
	v_pk_mul_f32 v[58:59], v[18:19], v[18:19]
	v_pk_add_f32 v[38:39], v[38:39], v[44:45]
	v_pk_mul_f32 v[42:43], v[62:63], v[42:43]
	v_lshlrev_b32_e32 v62, 16, v151
	v_and_b32_e32 v63, 0xffff0000, v151
	v_mul_f32_e32 v17, 0xbfb8aa3b, v66
	v_exp_f32_e32 v17, v17
	v_pk_add_f32 v[62:63], v[62:63], v[64:65]
	v_pk_mul_f32 v[44:45], v[38:39], v[38:39]
	v_pk_mul_f32 v[64:65], v[62:63], v[62:63]
	v_add_f32_e32 v17, 1.0, v17
	v_rcp_f32_e32 v68, v17
	v_mul_f32_e32 v17, 0xbfb8aa3b, v67
	v_exp_f32_e32 v17, v17
	s_nop 0
	v_add_f32_e32 v17, 1.0, v17
	v_rcp_f32_e32 v69, v17
	v_and_b32_e32 v17, 0xffff0000, v158
	v_pk_mul_f32 v[66:67], v[68:69], v[66:67]
	v_lshlrev_b32_e32 v68, 16, v150
	v_and_b32_e32 v69, 0xffff0000, v150
	v_lshlrev_b32_e32 v16, 16, v158
	v_lshlrev_b32_e32 v40, 16, v154
	v_mul_f32_e32 v21, 0xbfb8aa3b, v40
	v_exp_f32_e32 v21, v21
	v_pk_add_f32 v[16:17], v[68:69], v[16:17]
	v_add_f32_e32 v21, 1.0, v21
	v_rcp_f32_e32 v68, v21
	v_mul_f32_e32 v21, 0xbfb8aa3b, v41
	v_exp_f32_e32 v21, v21
	v_pk_mul_f32 v[56:57], v[16:17], v[16:17]
	v_add_f32_e32 v21, 1.0, v21
	v_rcp_f32_e32 v69, v21
	v_add_f32_e32 v21, v56, v57
	v_add_f32_e32 v21, v64, v21
	v_add_f32_e32 v21, v65, v21
	v_add_f32_e32 v21, v58, v21
	v_add_f32_e32 v21, v59, v21
	v_add_f32_e32 v21, v44, v21
	v_add_f32_e32 v21, v45, v21
	ds_bpermute_b32 v37, v49, v21
	v_pk_mul_f32 v[40:41], v[68:69], v[40:41]
	s_waitcnt lgkmcnt(0)
; __device__ __forceinline__ unsigned pk2(float lo, float hi) { const f32v2_t f = {lo, hi}; const bf16v2_t b = __builtin_convertvector(f, bf16v2_t); return __builtin_bit_cast(unsigned, b); }
; __device__ __forceinline__ float siluf(float v) { return v * __builtin_amdgcn_rcpf(1.f + __expf(-v)); }
; __device__ NOINL void combine_phase(const LAS Params* lp, int l, LAS unsigned char* lds) {
;     ...
;         for (int i = 0; i < 8; ++i) {
;             const size_t row = (size_t)(row0 + 8 * w + i);
;             float of[8], ob[8], zz[8];
;             unpack8(*(const u32x4*)(p.hbuf + row * DM + 256 + lane * 8), of); unpack8(*(const u32x4*)(p.hyproj + row * 768 + lane * 8), ob); unpack8(*(const u32x4*)(p.proj + row * 3072 + 1536 + lane * 8), zz);
;             float ss = 0.f;
; #pragma unroll
;             for (int e = 0; e < 8; ++e) { of[e] += ob[e]; ss += of[e] * of[e]; }
;             ss += __shfl_xor(ss, 1); ss += __shfl_xor(ss, 2); ss += __shfl_xor(ss, 4); ss += __shfl_xor(ss, 8);
;             const float inv = rsqrtf(ss * (1.f / 128.f) + 1e-6f);
;             float o[8];
; #pragma unroll
;             for (int e = 0; e < 8; ++e) o[e] = of[e] * inv * ng8[e] * siluf(zz[e]);
;             u32x4 pk; pk.x = pk2(o[0], o[1]); pk.y = pk2(o[2], o[3]); pk.z = pk2(o[4], o[5]); pk.w = pk2(o[6], o[7]);
;             *(u32x4*)(p.hbuf + row * DM + 256 + lane * 8) = pk;
;         }
	v_add_f32_e32 v21, v21, v37
	ds_bpermute_b32 v37, v50, v21
	s_waitcnt lgkmcnt(0)
	v_add_f32_e32 v21, v21, v37
	ds_bpermute_b32 v37, v51, v21
	s_waitcnt lgkmcnt(0)
	v_add_f32_e32 v21, v21, v37
	ds_bpermute_b32 v37, v52, v21
	s_waitcnt lgkmcnt(0)
	v_add_f32_e32 v21, v21, v37
	v_fmamk_f32 v21, v21, 0x3c000000, v211
	v_cmp_gt_f32_e32 vcc, s79, v21
	v_mul_f32_e32 v37, 0x4b800000, v21
	s_nop 0
	v_cndmask_b32_e32 v21, v21, v37, vcc
	v_rsq_f32_e32 v21, v21
	s_nop 0
	v_mul_f32_e32 v37, 0x45800000, v21
	v_cndmask_b32_e32 v44, v21, v37, vcc
	v_mul_f32_e32 v21, 0xbfb8aa3b, v60
	v_exp_f32_e32 v21, v21
	v_pk_mul_f32 v[18:19], v[18:19], v[44:45] op_sel_hi:[1,0]
	v_pk_mul_f32 v[16:17], v[16:17], v[44:45] op_sel_hi:[1,0]
	v_pk_mul_f32 v[18:19], v[8:9], v[18:19]
	v_add_f32_e32 v21, 1.0, v21
	v_pk_mul_f32 v[18:19], v[42:43], v[18:19]
	v_rcp_f32_e32 v42, v21
	v_mul_f32_e32 v21, 0xbfb8aa3b, v61
	v_exp_f32_e32 v21, v21
	v_pk_mul_f32 v[16:17], v[12:13], v[16:17]
	v_pk_mul_f32 v[38:39], v[38:39], v[44:45] op_sel_hi:[1,0]
	v_pk_mul_f32 v[16:17], v[40:41], v[16:17]
	v_add_f32_e32 v21, 1.0, v21
	v_rcp_f32_e32 v43, v21
	v_pk_mul_f32 v[40:41], v[62:63], v[44:45] op_sel_hi:[1,0]
	v_pk_mul_f32 v[38:39], v[10:11], v[38:39]
	v_pk_mul_f32 v[40:41], v[14:15], v[40:41]
	v_pk_mul_f32 v[42:43], v[42:43], v[60:61]
	v_pk_mul_f32 v[40:41], v[66:67], v[40:41]
	v_pk_mul_f32 v[38:39], v[42:43], v[38:39]
	v_cvt_pk_bf16_f32 v18, v18, v19
	v_cvt_pk_bf16_f32 v19, v38, v39
	v_cvt_pk_bf16_f32 v16, v16, v17
	v_cvt_pk_bf16_f32 v17, v40, v41
	global_store_dwordx4 v[148:149], v[16:19], off offset:512
	s_nop 0
	s_waitcnt vmcnt(23)
	v_lshlrev_b32_e32 v38, 16, v167
	v_and_b32_e32 v39, 0xffff0000, v167
	v_lshlrev_b32_e32 v62, 16, v166
	v_and_b32_e32 v63, 0xffff0000, v166
	s_waitcnt vmcnt(22)
	v_lshlrev_b32_e32 v66, 16, v169
	v_and_b32_e32 v67, 0xffff0000, v169
	v_lshlrev_b32_e32 v60, 16, v171
	v_and_b32_e32 v61, 0xffff0000, v171
	s_waitcnt vmcnt(21)
	v_lshlrev_b32_e32 v18, 16, v174
	v_and_b32_e32 v19, 0xffff0000, v174
	v_lshlrev_b32_e32 v42, 16, v170
	v_mul_f32_e32 v21, 0xbfb8aa3b, v42
	v_exp_f32_e32 v21, v21
	v_lshlrev_b32_e32 v44, 16, v175
	v_and_b32_e32 v45, 0xffff0000, v175
	v_and_b32_e32 v43, 0xffff0000, v170
	v_add_f32_e32 v21, 1.0, v21
	v_pk_add_f32 v[18:19], v[62:63], v[18:19]
	v_rcp_f32_e32 v62, v21
	v_mul_f32_e32 v21, 0xbfb8aa3b, v43
	v_exp_f32_e32 v21, v21
	v_lshlrev_b32_e32 v64, 16, v173
	v_and_b32_e32 v65, 0xffff0000, v173
	v_and_b32_e32 v41, 0xffff0000, v168
	v_add_f32_e32 v21, 1.0, v21
	v_rcp_f32_e32 v63, v21
	v_pk_mul_f32 v[58:59], v[18:19], v[18:19]
	v_pk_add_f32 v[38:39], v[38:39], v[44:45]
	v_pk_mul_f32 v[42:43], v[62:63], v[42:43]
	v_lshlrev_b32_e32 v62, 16, v165
	v_and_b32_e32 v63, 0xffff0000, v165
	v_mul_f32_e32 v17, 0xbfb8aa3b, v66
	v_exp_f32_e32 v17, v17
	v_pk_add_f32 v[62:63], v[62:63], v[64:65]
	v_pk_mul_f32 v[44:45], v[38:39], v[38:39]
	v_pk_mul_f32 v[64:65], v[62:63], v[62:63]
	v_add_f32_e32 v17, 1.0, v17
	v_rcp_f32_e32 v68, v17
	v_mul_f32_e32 v17, 0xbfb8aa3b, v67
	v_exp_f32_e32 v17, v17
	s_nop 0
	v_add_f32_e32 v17, 1.0, v17
	v_rcp_f32_e32 v69, v17
	v_and_b32_e32 v17, 0xffff0000, v172
	v_pk_mul_f32 v[66:67], v[68:69], v[66:67]
	v_lshlrev_b32_e32 v68, 16, v164
	v_and_b32_e32 v69, 0xffff0000, v164
	v_lshlrev_b32_e32 v16, 16, v172
	v_lshlrev_b32_e32 v40, 16, v168
	v_mul_f32_e32 v21, 0xbfb8aa3b, v40
	v_exp_f32_e32 v21, v21
	v_pk_add_f32 v[16:17], v[68:69], v[16:17]
	v_add_f32_e32 v21, 1.0, v21
	v_rcp_f32_e32 v68, v21
	v_mul_f32_e32 v21, 0xbfb8aa3b, v41
	v_exp_f32_e32 v21, v21
	v_pk_mul_f32 v[56:57], v[16:17], v[16:17]
	v_add_f32_e32 v21, 1.0, v21
	v_rcp_f32_e32 v69, v21
	v_add_f32_e32 v21, v56, v57
	v_add_f32_e32 v21, v64, v21
	v_add_f32_e32 v21, v65, v21
	v_add_f32_e32 v21, v58, v21
	v_add_f32_e32 v21, v59, v21
	v_add_f32_e32 v21, v44, v21
	v_add_f32_e32 v21, v45, v21
	ds_bpermute_b32 v37, v49, v21
	v_pk_mul_f32 v[40:41], v[68:69], v[40:41]
	s_waitcnt lgkmcnt(0)
	v_add_f32_e32 v21, v21, v37
	ds_bpermute_b32 v37, v50, v21
	s_waitcnt lgkmcnt(0)
	v_add_f32_e32 v21, v21, v37
	ds_bpermute_b32 v37, v51, v21
	s_waitcnt lgkmcnt(0)
	v_add_f32_e32 v21, v21, v37
	ds_bpermute_b32 v37, v52, v21
	s_waitcnt lgkmcnt(0)
	v_add_f32_e32 v21, v21, v37
	v_fmamk_f32 v21, v21, 0x3c000000, v211
	v_cmp_gt_f32_e32 vcc, s79, v21
	v_mul_f32_e32 v37, 0x4b800000, v21
	s_nop 0
	v_cndmask_b32_e32 v21, v21, v37, vcc
	v_rsq_f32_e32 v21, v21
	s_nop 0
	v_mul_f32_e32 v37, 0x45800000, v21
	v_cndmask_b32_e32 v44, v21, v37, vcc
	v_mul_f32_e32 v21, 0xbfb8aa3b, v60
	v_exp_f32_e32 v21, v21
	v_pk_mul_f32 v[18:19], v[18:19], v[44:45] op_sel_hi:[1,0]
	v_pk_mul_f32 v[16:17], v[16:17], v[44:45] op_sel_hi:[1,0]
	v_pk_mul_f32 v[18:19], v[8:9], v[18:19]
	v_add_f32_e32 v21, 1.0, v21
	v_pk_mul_f32 v[18:19], v[42:43], v[18:19]
	v_rcp_f32_e32 v42, v21
	v_mul_f32_e32 v21, 0xbfb8aa3b, v61
	v_exp_f32_e32 v21, v21
	v_pk_mul_f32 v[16:17], v[12:13], v[16:17]
	v_pk_mul_f32 v[38:39], v[38:39], v[44:45] op_sel_hi:[1,0]
	v_pk_mul_f32 v[16:17], v[40:41], v[16:17]
	v_add_f32_e32 v21, 1.0, v21
	v_rcp_f32_e32 v43, v21
	v_pk_mul_f32 v[40:41], v[62:63], v[44:45] op_sel_hi:[1,0]
	v_pk_mul_f32 v[38:39], v[10:11], v[38:39]
	v_pk_mul_f32 v[40:41], v[14:15], v[40:41]
	v_pk_mul_f32 v[42:43], v[42:43], v[60:61]
	v_pk_mul_f32 v[40:41], v[66:67], v[40:41]
	v_pk_mul_f32 v[38:39], v[42:43], v[38:39]
	v_cvt_pk_bf16_f32 v16, v16, v17
	v_cvt_pk_bf16_f32 v17, v40, v41
	v_cvt_pk_bf16_f32 v18, v18, v19
	v_cvt_pk_bf16_f32 v19, v38, v39
	global_store_dwordx4 v[162:163], v[16:19], off offset:512
	s_waitcnt vmcnt(21)
	v_lshlrev_b32_e32 v22, 16, v179
	v_and_b32_e32 v23, 0xffff0000, v179
	v_lshlrev_b32_e32 v60, 16, v178
	v_and_b32_e32 v61, 0xffff0000, v178
	s_waitcnt vmcnt(20)
; __device__ NOINL void combine_phase(const LAS Params* lp, int l, LAS unsigned char* lds) {
;     ...
;         for (int i = 0; i < 8; ++i) {
;             const size_t row = (size_t)(row0 + 8 * w + i);
;             float of[8], ob[8], zz[8];
;             unpack8(*(const u32x4*)(p.hbuf + row * DM + 256 + lane * 8), of); unpack8(*(const u32x4*)(p.hyproj + row * 768 + lane * 8), ob); unpack8(*(const u32x4*)(p.proj + row * 3072 + 1536 + lane * 8), zz);
;             float ss = 0.f;
; #pragma unroll
;             for (int e = 0; e < 8; ++e) { of[e] += ob[e]; ss += of[e] * of[e]; }
;             ss += __shfl_xor(ss, 1); ss += __shfl_xor(ss, 2); ss += __shfl_xor(ss, 4); ss += __shfl_xor(ss, 8);
;             const float inv = rsqrtf(ss * (1.f / 128.f) + 1e-6f);
;             float o[8];
; #pragma unroll
;             for (int e = 0; e < 8; ++e) o[e] = of[e] * inv * ng8[e] * siluf(zz[e]);
;             u32x4 pk; pk.x = pk2(o[0], o[1]); pk.y = pk2(o[2], o[3]); pk.z = pk2(o[4], o[5]); pk.w = pk2(o[6], o[7]);
;             *(u32x4*)(p.hbuf + row * DM + 256 + lane * 8) = pk;
;         }
; #pragma unroll
;         for (int i = 0; i < 4; ++i) {
;             const size_t row = (size_t)(row0 + 8 * w + 2 * i + (lane >> 5)); const int l32 = lane & 31;
;             float of[8], ob[8], gg[8];
;             unpack8(*(const u32x4*)(p.hbuf + row * DM + 768 + l32 * 8), of); unpack8(*(const u32x4*)(p.hyproj + row * 768 + 512 + l32 * 8), ob); unpack8(*(const u32x4*)(p.proj + row * 3072 + 2816 + l32 * 8), gg);
;             float s1 = 0.f;
; #pragma unroll
;             for (int e = 0; e < 8; ++e) { of[e] += ob[e]; s1 += of[e]; }
;             s1 += __shfl_xor(s1, 1); s1 += __shfl_xor(s1, 2); s1 += __shfl_xor(s1, 4);
;             const float mu = s1 * (1.f / 64.f); float s2 = 0.f;
; #pragma unroll
;             for (int e = 0; e < 8; ++e) { of[e] -= mu; s2 += of[e] * of[e]; }
;             s2 += __shfl_xor(s2, 1); s2 += __shfl_xor(s2, 2); s2 += __shfl_xor(s2, 4);
;             const float inv = rsqrtf(s2 * (1.f / 64.f) + 1e-6f);
;             float o[8];
; #pragma unroll
;             for (int e = 0; e < 8; ++e) o[e] = of[e] * inv * siluf(gg[e]);
;             u32x4 pk; pk.x = pk2(o[0], o[1]); pk.y = pk2(o[2], o[3]); pk.z = pk2(o[4], o[5]); pk.w = pk2(o[6], o[7]);
;             *(u32x4*)(p.hbuf + row * DM + 768 + l32 * 8) = pk;
;         }
	v_lshlrev_b32_e32 v64, 16, v181
	v_and_b32_e32 v65, 0xffff0000, v181
	v_lshlrev_b32_e32 v58, 16, v183
	v_and_b32_e32 v59, 0xffff0000, v183
	s_waitcnt vmcnt(19)
	v_lshlrev_b32_e32 v18, 16, v188
	v_and_b32_e32 v19, 0xffff0000, v188
	v_lshlrev_b32_e32 v40, 16, v182
	v_mul_f32_e32 v37, 0xbfb8aa3b, v40
	v_exp_f32_e32 v37, v37
	v_lshlrev_b32_e32 v56, 16, v189
	v_and_b32_e32 v57, 0xffff0000, v189
	v_and_b32_e32 v41, 0xffff0000, v182
	v_add_f32_e32 v37, 1.0, v37
	v_pk_add_f32 v[18:19], v[60:61], v[18:19]
	v_rcp_f32_e32 v60, v37
	v_mul_f32_e32 v37, 0xbfb8aa3b, v41
	v_exp_f32_e32 v37, v37
	v_lshlrev_b32_e32 v62, 16, v187
	v_and_b32_e32 v63, 0xffff0000, v187
	v_and_b32_e32 v39, 0xffff0000, v180
	v_add_f32_e32 v37, 1.0, v37
	v_rcp_f32_e32 v61, v37
	v_pk_mul_f32 v[44:45], v[18:19], v[18:19]
	v_pk_add_f32 v[22:23], v[22:23], v[56:57]
	v_pk_mul_f32 v[40:41], v[60:61], v[40:41]
	v_lshlrev_b32_e32 v60, 16, v177
	v_and_b32_e32 v61, 0xffff0000, v177
	v_mul_f32_e32 v17, 0xbfb8aa3b, v64
	v_exp_f32_e32 v17, v17
	v_pk_add_f32 v[60:61], v[60:61], v[62:63]
	v_pk_mul_f32 v[56:57], v[22:23], v[22:23]
	v_pk_mul_f32 v[62:63], v[60:61], v[60:61]
	v_add_f32_e32 v17, 1.0, v17
	v_rcp_f32_e32 v66, v17
	v_mul_f32_e32 v17, 0xbfb8aa3b, v65
	v_exp_f32_e32 v17, v17
	s_nop 0
	v_add_f32_e32 v17, 1.0, v17
	v_rcp_f32_e32 v67, v17
	v_and_b32_e32 v17, 0xffff0000, v186
	v_pk_mul_f32 v[64:65], v[66:67], v[64:65]
	v_lshlrev_b32_e32 v66, 16, v176
	v_and_b32_e32 v67, 0xffff0000, v176
	v_lshlrev_b32_e32 v16, 16, v186
	v_lshlrev_b32_e32 v38, 16, v180
	v_mul_f32_e32 v37, 0xbfb8aa3b, v38
	v_exp_f32_e32 v37, v37
	v_pk_add_f32 v[16:17], v[66:67], v[16:17]
	v_add_f32_e32 v37, 1.0, v37
	v_rcp_f32_e32 v66, v37
	v_mul_f32_e32 v37, 0xbfb8aa3b, v39
	v_exp_f32_e32 v37, v37
	v_pk_mul_f32 v[42:43], v[16:17], v[16:17]
	v_add_f32_e32 v37, 1.0, v37
	v_rcp_f32_e32 v67, v37
	v_add_f32_e32 v37, v42, v43
	v_add_f32_e32 v37, v62, v37
	v_add_f32_e32 v37, v63, v37
	v_add_f32_e32 v37, v44, v37
	v_add_f32_e32 v37, v45, v37
	v_add_f32_e32 v37, v56, v37
	v_add_f32_e32 v37, v57, v37
	ds_bpermute_b32 v42, v49, v37
	v_pk_mul_f32 v[38:39], v[66:67], v[38:39]
	s_waitcnt lgkmcnt(0)
	v_add_f32_e32 v37, v37, v42
	ds_bpermute_b32 v42, v50, v37
	s_waitcnt lgkmcnt(0)
	v_add_f32_e32 v37, v37, v42
	ds_bpermute_b32 v42, v51, v37
	s_waitcnt lgkmcnt(0)
	v_add_f32_e32 v37, v37, v42
	ds_bpermute_b32 v42, v52, v37
	s_waitcnt lgkmcnt(0)
	v_add_f32_e32 v37, v37, v42
	v_fmamk_f32 v37, v37, 0x3c000000, v211
	v_cmp_gt_f32_e32 vcc, s79, v37
	v_mul_f32_e32 v42, 0x4b800000, v37
	s_nop 0
	v_cndmask_b32_e32 v37, v37, v42, vcc
	v_rsq_f32_e32 v37, v37
	s_nop 0
	v_mul_f32_e32 v42, 0x45800000, v37
	v_cndmask_b32_e32 v42, v37, v42, vcc
	v_mul_f32_e32 v37, 0xbfb8aa3b, v58
	v_exp_f32_e32 v37, v37
	v_pk_mul_f32 v[18:19], v[18:19], v[42:43] op_sel_hi:[1,0]
	v_pk_mul_f32 v[16:17], v[16:17], v[42:43] op_sel_hi:[1,0]
	v_pk_mul_f32 v[18:19], v[8:9], v[18:19]
	v_add_f32_e32 v37, 1.0, v37
	v_pk_mul_f32 v[18:19], v[40:41], v[18:19]
	v_rcp_f32_e32 v40, v37
	v_mul_f32_e32 v37, 0xbfb8aa3b, v59
	v_exp_f32_e32 v37, v37
	v_pk_mul_f32 v[16:17], v[12:13], v[16:17]
	v_pk_mul_f32 v[22:23], v[22:23], v[42:43] op_sel_hi:[1,0]
	v_pk_mul_f32 v[16:17], v[38:39], v[16:17]
	v_add_f32_e32 v37, 1.0, v37
	v_rcp_f32_e32 v41, v37
	v_pk_mul_f32 v[38:39], v[60:61], v[42:43] op_sel_hi:[1,0]
	v_pk_mul_f32 v[22:23], v[10:11], v[22:23]
	v_pk_mul_f32 v[38:39], v[14:15], v[38:39]
	v_pk_mul_f32 v[40:41], v[40:41], v[58:59]
	v_pk_mul_f32 v[38:39], v[64:65], v[38:39]
	v_pk_mul_f32 v[22:23], v[40:41], v[22:23]
	v_cvt_pk_bf16_f32 v16, v16, v17
	v_cvt_pk_bf16_f32 v17, v38, v39
	v_cvt_pk_bf16_f32 v18, v18, v19
	v_cvt_pk_bf16_f32 v19, v22, v23
	global_store_dwordx4 v[76:77], v[16:19], off offset:512
	s_nop 0
	s_waitcnt vmcnt(14)
	v_lshlrev_b32_e32 v60, 16, v93
	v_lshlrev_b32_e32 v44, 16, v89
	v_and_b32_e32 v45, 0xffff0000, v89
	v_and_b32_e32 v61, 0xffff0000, v93
	v_pk_add_f32 v[44:45], v[44:45], v[60:61]
	v_lshlrev_b32_e32 v60, 16, v88
	v_and_b32_e32 v61, 0xffff0000, v88
	v_lshlrev_b32_e32 v18, 16, v92
	v_and_b32_e32 v19, 0xffff0000, v92
	v_pk_add_f32 v[18:19], v[60:61], v[18:19]
	v_lshlrev_b32_e32 v60, 16, v91
	v_and_b32_e32 v61, 0xffff0000, v91
	s_waitcnt vmcnt(13)
	v_lshlrev_b32_e32 v22, 16, v96
	v_mul_f32_e32 v39, 0xbfb8aa3b, v22
	v_exp_f32_e32 v39, v39
	v_and_b32_e32 v23, 0xffff0000, v96
	v_lshlrev_b32_e32 v62, 16, v97
	v_and_b32_e32 v63, 0xffff0000, v97
	v_add_f32_e32 v39, 1.0, v39
	v_rcp_f32_e32 v58, v39
	v_mul_f32_e32 v39, 0xbfb8aa3b, v23
	v_exp_f32_e32 v39, v39
	v_lshlrev_b32_e32 v64, 16, v95
	v_and_b32_e32 v65, 0xffff0000, v95
	v_and_b32_e32 v21, 0xffff0000, v94
	v_add_f32_e32 v39, 1.0, v39
	v_rcp_f32_e32 v59, v39
	s_nop 0
	v_pk_mul_f32 v[22:23], v[58:59], v[22:23]
	v_lshlrev_b32_e32 v58, 16, v87
	v_and_b32_e32 v59, 0xffff0000, v87
	v_mul_f32_e32 v17, 0xbfb8aa3b, v64
	v_exp_f32_e32 v17, v17
	v_pk_add_f32 v[58:59], v[58:59], v[60:61]
	v_add_f32_e32 v17, 1.0, v17
	v_rcp_f32_e32 v60, v17
	v_mul_f32_e32 v17, 0xbfb8aa3b, v65
	v_exp_f32_e32 v17, v17
	s_nop 0
	v_add_f32_e32 v17, 1.0, v17
	v_rcp_f32_e32 v61, v17
	v_and_b32_e32 v17, 0xffff0000, v90
	v_pk_mul_f32 v[60:61], v[60:61], v[64:65]
	v_lshlrev_b32_e32 v64, 16, v86
	v_and_b32_e32 v65, 0xffff0000, v86
	v_lshlrev_b32_e32 v16, 16, v90
	v_lshlrev_b32_e32 v20, 16, v94
	v_mul_f32_e32 v55, 0xbfb8aa3b, v20
	v_exp_f32_e32 v55, v55
	v_pk_add_f32 v[16:17], v[64:65], v[16:17]
	v_add_f32_e32 v55, 1.0, v55
	v_add_f32_e32 v39, 0, v16
	v_add_f32_e32 v39, v17, v39
	v_rcp_f32_e32 v56, v55
	v_mul_f32_e32 v55, 0xbfb8aa3b, v21
	v_add_f32_e32 v39, v58, v39
	v_exp_f32_e32 v55, v55
	v_add_f32_e32 v39, v59, v39
	v_add_f32_e32 v39, v18, v39
	v_add_f32_e32 v39, v19, v39
	v_add_f32_e32 v39, v44, v39
	v_add_f32_e32 v55, 1.0, v55
	v_add_f32_e32 v39, v45, v39
	v_rcp_f32_e32 v57, v55
	ds_bpermute_b32 v55, v49, v39
	v_pk_mul_f32 v[20:21], v[56:57], v[20:21]
	s_waitcnt lgkmcnt(0)
; __device__ __forceinline__ unsigned pk2(float lo, float hi) { const f32v2_t f = {lo, hi}; const bf16v2_t b = __builtin_convertvector(f, bf16v2_t); return __builtin_bit_cast(unsigned, b); }
; __device__ __forceinline__ float siluf(float v) { return v * __builtin_amdgcn_rcpf(1.f + __expf(-v)); }
; __device__ NOINL void combine_phase(const LAS Params* lp, int l, LAS unsigned char* lds) {
;     ...
;         for (int i = 0; i < 4; ++i) {
;             const size_t row = (size_t)(row0 + 8 * w + 2 * i + (lane >> 5)); const int l32 = lane & 31;
;             float of[8], ob[8], gg[8];
;             unpack8(*(const u32x4*)(p.hbuf + row * DM + 768 + l32 * 8), of); unpack8(*(const u32x4*)(p.hyproj + row * 768 + 512 + l32 * 8), ob); unpack8(*(const u32x4*)(p.proj + row * 3072 + 2816 + l32 * 8), gg);
;             float s1 = 0.f;
; #pragma unroll
;             for (int e = 0; e < 8; ++e) { of[e] += ob[e]; s1 += of[e]; }
;             s1 += __shfl_xor(s1, 1); s1 += __shfl_xor(s1, 2); s1 += __shfl_xor(s1, 4);
;             const float mu = s1 * (1.f / 64.f); float s2 = 0.f;
; #pragma unroll
;             for (int e = 0; e < 8; ++e) { of[e] -= mu; s2 += of[e] * of[e]; }
;             s2 += __shfl_xor(s2, 1); s2 += __shfl_xor(s2, 2); s2 += __shfl_xor(s2, 4);
;             const float inv = rsqrtf(s2 * (1.f / 64.f) + 1e-6f);
;             float o[8];
; #pragma unroll
;             for (int e = 0; e < 8; ++e) o[e] = of[e] * inv * siluf(gg[e]);
;             u32x4 pk; pk.x = pk2(o[0], o[1]); pk.y = pk2(o[2], o[3]); pk.z = pk2(o[4], o[5]); pk.w = pk2(o[6], o[7]);
;             *(u32x4*)(p.hbuf + row * DM + 768 + l32 * 8) = pk;
;         }
	v_add_f32_e32 v39, v39, v55
	ds_bpermute_b32 v55, v50, v39
	s_waitcnt lgkmcnt(0)
	v_add_f32_e32 v39, v39, v55
	ds_bpermute_b32 v55, v51, v39
	s_waitcnt lgkmcnt(0)
	v_add_f32_e32 v39, v39, v55
	v_mul_f32_e32 v56, 0x3c800000, v39
	v_pk_add_f32 v[16:17], v[16:17], v[56:57] op_sel_hi:[1,0] neg_lo:[0,1] neg_hi:[0,1]
	v_pk_add_f32 v[58:59], v[58:59], v[56:57] op_sel_hi:[1,0] neg_lo:[0,1] neg_hi:[0,1]
	v_pk_mul_f32 v[64:65], v[16:17], v[16:17]
	v_pk_mul_f32 v[66:67], v[58:59], v[58:59]
	v_add_f32_e32 v39, v64, v65
	v_pk_add_f32 v[18:19], v[18:19], v[56:57] op_sel_hi:[1,0] neg_lo:[0,1] neg_hi:[0,1]
	v_add_f32_e32 v39, v66, v39
	v_pk_mul_f32 v[68:69], v[18:19], v[18:19]
	v_add_f32_e32 v39, v67, v39
	v_pk_add_f32 v[44:45], v[44:45], v[56:57] op_sel_hi:[1,0] neg_lo:[0,1] neg_hi:[0,1]
	v_add_f32_e32 v39, v68, v39
	v_pk_mul_f32 v[56:57], v[44:45], v[44:45]
	v_add_f32_e32 v39, v69, v39
	v_add_f32_e32 v39, v56, v39
	v_add_f32_e32 v39, v57, v39
	ds_bpermute_b32 v55, v49, v39
	s_waitcnt lgkmcnt(0)
	v_add_f32_e32 v39, v39, v55
	ds_bpermute_b32 v55, v50, v39
	s_waitcnt lgkmcnt(0)
	v_add_f32_e32 v39, v39, v55
	ds_bpermute_b32 v55, v51, v39
	s_waitcnt lgkmcnt(0)
	v_add_f32_e32 v39, v39, v55
	v_fmamk_f32 v39, v39, 0x3c800000, v211
	v_cmp_gt_f32_e32 vcc, s79, v39
	v_mul_f32_e32 v55, 0x4b800000, v39
	s_nop 0
	v_cndmask_b32_e32 v39, v39, v55, vcc
	v_rsq_f32_e32 v39, v39
	s_nop 0
	v_mul_f32_e32 v55, 0x45800000, v39
	v_cndmask_b32_e32 v56, v39, v55, vcc
	v_pk_mul_f32 v[18:19], v[18:19], v[56:57] op_sel_hi:[1,0]
	v_pk_mul_f32 v[16:17], v[16:17], v[56:57] op_sel_hi:[1,0]
	v_pk_mul_f32 v[18:19], v[22:23], v[18:19]
	v_mul_f32_e32 v22, 0xbfb8aa3b, v62
	v_mul_f32_e32 v23, 0xbfb8aa3b, v63
	v_exp_f32_e32 v22, v22
	v_exp_f32_e32 v23, v23
	v_pk_mul_f32 v[16:17], v[20:21], v[16:17]
	v_pk_mul_f32 v[20:21], v[58:59], v[56:57] op_sel_hi:[1,0]
	v_add_f32_e32 v22, 1.0, v22
	v_add_f32_e32 v23, 1.0, v23
	v_rcp_f32_e32 v22, v22
	v_rcp_f32_e32 v23, v23
	v_pk_mul_f32 v[44:45], v[44:45], v[56:57] op_sel_hi:[1,0]
	v_pk_mul_f32 v[20:21], v[60:61], v[20:21]
	v_cvt_pk_bf16_f32 v16, v16, v17
	v_pk_mul_f32 v[22:23], v[22:23], v[62:63]
	v_cvt_pk_bf16_f32 v17, v20, v21
	v_pk_mul_f32 v[22:23], v[22:23], v[44:45]
	v_cvt_pk_bf16_f32 v18, v18, v19
	v_cvt_pk_bf16_f32 v19, v22, v23
	global_store_dwordx4 v[84:85], v[16:19], off offset:1536
	s_nop 0
	s_nop 0
	s_waitcnt vmcnt(12)
	v_lshlrev_b32_e32 v60, 16, v107
	v_lshlrev_b32_e32 v44, 16, v103
	v_and_b32_e32 v45, 0xffff0000, v103
	v_and_b32_e32 v61, 0xffff0000, v107
	v_pk_add_f32 v[44:45], v[44:45], v[60:61]
	v_lshlrev_b32_e32 v60, 16, v102
	v_and_b32_e32 v61, 0xffff0000, v102
	v_lshlrev_b32_e32 v18, 16, v106
	v_and_b32_e32 v19, 0xffff0000, v106
	v_pk_add_f32 v[18:19], v[60:61], v[18:19]
	v_lshlrev_b32_e32 v60, 16, v105
	v_and_b32_e32 v61, 0xffff0000, v105
	s_waitcnt vmcnt(11)
	v_lshlrev_b32_e32 v22, 16, v110
	v_mul_f32_e32 v39, 0xbfb8aa3b, v22
	v_exp_f32_e32 v39, v39
	v_and_b32_e32 v23, 0xffff0000, v110
	v_lshlrev_b32_e32 v62, 16, v111
	v_and_b32_e32 v63, 0xffff0000, v111
	v_add_f32_e32 v39, 1.0, v39
	v_rcp_f32_e32 v58, v39
	v_mul_f32_e32 v39, 0xbfb8aa3b, v23
	v_exp_f32_e32 v39, v39
	v_lshlrev_b32_e32 v64, 16, v109
	v_and_b32_e32 v65, 0xffff0000, v109
	v_and_b32_e32 v21, 0xffff0000, v108
	v_add_f32_e32 v39, 1.0, v39
	v_rcp_f32_e32 v59, v39
	s_nop 0
	v_pk_mul_f32 v[22:23], v[58:59], v[22:23]
	v_lshlrev_b32_e32 v58, 16, v101
	v_and_b32_e32 v59, 0xffff0000, v101
	v_mul_f32_e32 v17, 0xbfb8aa3b, v64
	v_exp_f32_e32 v17, v17
	v_pk_add_f32 v[58:59], v[58:59], v[60:61]
	v_add_f32_e32 v17, 1.0, v17
	v_rcp_f32_e32 v60, v17
	v_mul_f32_e32 v17, 0xbfb8aa3b, v65
	v_exp_f32_e32 v17, v17
	s_nop 0
	v_add_f32_e32 v17, 1.0, v17
	v_rcp_f32_e32 v61, v17
	v_and_b32_e32 v17, 0xffff0000, v104
	v_pk_mul_f32 v[60:61], v[60:61], v[64:65]
	v_lshlrev_b32_e32 v64, 16, v100
	v_and_b32_e32 v65, 0xffff0000, v100
	v_lshlrev_b32_e32 v16, 16, v104
	v_lshlrev_b32_e32 v20, 16, v108
	v_mul_f32_e32 v55, 0xbfb8aa3b, v20
	v_exp_f32_e32 v55, v55
	v_pk_add_f32 v[16:17], v[64:65], v[16:17]
	v_add_f32_e32 v55, 1.0, v55
	v_add_f32_e32 v39, 0, v16
	v_add_f32_e32 v39, v17, v39
	v_rcp_f32_e32 v56, v55
	v_mul_f32_e32 v55, 0xbfb8aa3b, v21
	v_add_f32_e32 v39, v58, v39
	v_exp_f32_e32 v55, v55
	v_add_f32_e32 v39, v59, v39
	v_add_f32_e32 v39, v18, v39
	v_add_f32_e32 v39, v19, v39
	v_add_f32_e32 v39, v44, v39
	v_add_f32_e32 v55, 1.0, v55
	v_add_f32_e32 v39, v45, v39
	v_rcp_f32_e32 v57, v55
	ds_bpermute_b32 v55, v49, v39
	v_pk_mul_f32 v[20:21], v[56:57], v[20:21]
	s_waitcnt lgkmcnt(0)
	v_add_f32_e32 v39, v39, v55
	ds_bpermute_b32 v55, v50, v39
	s_waitcnt lgkmcnt(0)
	v_add_f32_e32 v39, v39, v55
	ds_bpermute_b32 v55, v51, v39
	s_waitcnt lgkmcnt(0)
	v_add_f32_e32 v39, v39, v55
	v_mul_f32_e32 v56, 0x3c800000, v39
	v_pk_add_f32 v[16:17], v[16:17], v[56:57] op_sel_hi:[1,0] neg_lo:[0,1] neg_hi:[0,1]
	v_pk_add_f32 v[58:59], v[58:59], v[56:57] op_sel_hi:[1,0] neg_lo:[0,1] neg_hi:[0,1]
	v_pk_mul_f32 v[64:65], v[16:17], v[16:17]
	v_pk_mul_f32 v[66:67], v[58:59], v[58:59]
	v_add_f32_e32 v39, v64, v65
	v_pk_add_f32 v[18:19], v[18:19], v[56:57] op_sel_hi:[1,0] neg_lo:[0,1] neg_hi:[0,1]
	v_add_f32_e32 v39, v66, v39
	v_pk_mul_f32 v[68:69], v[18:19], v[18:19]
	v_add_f32_e32 v39, v67, v39
	v_pk_add_f32 v[44:45], v[44:45], v[56:57] op_sel_hi:[1,0] neg_lo:[0,1] neg_hi:[0,1]
	v_add_f32_e32 v39, v68, v39
	v_pk_mul_f32 v[56:57], v[44:45], v[44:45]
	v_add_f32_e32 v39, v69, v39
	v_add_f32_e32 v39, v56, v39
	v_add_f32_e32 v39, v57, v39
	ds_bpermute_b32 v55, v49, v39
	s_waitcnt lgkmcnt(0)
	v_add_f32_e32 v39, v39, v55
	ds_bpermute_b32 v55, v50, v39
	s_waitcnt lgkmcnt(0)
	v_add_f32_e32 v39, v39, v55
	ds_bpermute_b32 v55, v51, v39
	s_waitcnt lgkmcnt(0)
; __device__ __forceinline__ unsigned pk2(float lo, float hi) { const f32v2_t f = {lo, hi}; const bf16v2_t b = __builtin_convertvector(f, bf16v2_t); return __builtin_bit_cast(unsigned, b); }
; __device__ __forceinline__ float siluf(float v) { return v * __builtin_amdgcn_rcpf(1.f + __expf(-v)); }
; __device__ NOINL void combine_phase(const LAS Params* lp, int l, LAS unsigned char* lds) {
;     ...
;         for (int i = 0; i < 4; ++i) {
;             const size_t row = (size_t)(row0 + 8 * w + 2 * i + (lane >> 5)); const int l32 = lane & 31;
;             float of[8], ob[8], gg[8];
;             unpack8(*(const u32x4*)(p.hbuf + row * DM + 768 + l32 * 8), of); unpack8(*(const u32x4*)(p.hyproj + row * 768 + 512 + l32 * 8), ob); unpack8(*(const u32x4*)(p.proj + row * 3072 + 2816 + l32 * 8), gg);
;             float s1 = 0.f;
; #pragma unroll
;             for (int e = 0; e < 8; ++e) { of[e] += ob[e]; s1 += of[e]; }
;             s1 += __shfl_xor(s1, 1); s1 += __shfl_xor(s1, 2); s1 += __shfl_xor(s1, 4);
;             const float mu = s1 * (1.f / 64.f); float s2 = 0.f;
; #pragma unroll
;             for (int e = 0; e < 8; ++e) { of[e] -= mu; s2 += of[e] * of[e]; }
;             s2 += __shfl_xor(s2, 1); s2 += __shfl_xor(s2, 2); s2 += __shfl_xor(s2, 4);
;             const float inv = rsqrtf(s2 * (1.f / 64.f) + 1e-6f);
;             float o[8];
; #pragma unroll
;             for (int e = 0; e < 8; ++e) o[e] = of[e] * inv * siluf(gg[e]);
;             u32x4 pk; pk.x = pk2(o[0], o[1]); pk.y = pk2(o[2], o[3]); pk.z = pk2(o[4], o[5]); pk.w = pk2(o[6], o[7]);
;             *(u32x4*)(p.hbuf + row * DM + 768 + l32 * 8) = pk;
;         }
	v_add_f32_e32 v39, v39, v55
	v_fmamk_f32 v39, v39, 0x3c800000, v211
	v_cmp_gt_f32_e32 vcc, s79, v39
	v_mul_f32_e32 v55, 0x4b800000, v39
	s_nop 0
	v_cndmask_b32_e32 v39, v39, v55, vcc
	v_rsq_f32_e32 v39, v39
	s_nop 0
	v_mul_f32_e32 v55, 0x45800000, v39
	v_cndmask_b32_e32 v56, v39, v55, vcc
	v_pk_mul_f32 v[18:19], v[18:19], v[56:57] op_sel_hi:[1,0]
	v_pk_mul_f32 v[16:17], v[16:17], v[56:57] op_sel_hi:[1,0]
	v_pk_mul_f32 v[18:19], v[22:23], v[18:19]
	v_mul_f32_e32 v22, 0xbfb8aa3b, v62
	v_mul_f32_e32 v23, 0xbfb8aa3b, v63
	v_exp_f32_e32 v22, v22
	v_exp_f32_e32 v23, v23
	v_pk_mul_f32 v[16:17], v[20:21], v[16:17]
	v_pk_mul_f32 v[20:21], v[58:59], v[56:57] op_sel_hi:[1,0]
	v_add_f32_e32 v22, 1.0, v22
	v_add_f32_e32 v23, 1.0, v23
	v_rcp_f32_e32 v22, v22
	v_rcp_f32_e32 v23, v23
	v_pk_mul_f32 v[44:45], v[44:45], v[56:57] op_sel_hi:[1,0]
	v_pk_mul_f32 v[20:21], v[60:61], v[20:21]
	v_cvt_pk_bf16_f32 v16, v16, v17
	v_pk_mul_f32 v[22:23], v[22:23], v[62:63]
	v_cvt_pk_bf16_f32 v17, v20, v21
	v_pk_mul_f32 v[22:23], v[22:23], v[44:45]
	v_cvt_pk_bf16_f32 v18, v18, v19
	v_cvt_pk_bf16_f32 v19, v22, v23
	global_store_dwordx4 v[98:99], v[16:19], off offset:1536
	s_nop 0
	s_nop 0
	s_waitcnt vmcnt(10)
	v_lshlrev_b32_e32 v60, 16, v121
	v_lshlrev_b32_e32 v44, 16, v117
	v_and_b32_e32 v45, 0xffff0000, v117
	v_and_b32_e32 v61, 0xffff0000, v121
	v_pk_add_f32 v[44:45], v[44:45], v[60:61]
	v_lshlrev_b32_e32 v60, 16, v116
	v_and_b32_e32 v61, 0xffff0000, v116
	v_lshlrev_b32_e32 v18, 16, v120
	v_and_b32_e32 v19, 0xffff0000, v120
	v_pk_add_f32 v[18:19], v[60:61], v[18:19]
	v_lshlrev_b32_e32 v60, 16, v119
	v_and_b32_e32 v61, 0xffff0000, v119
	s_waitcnt vmcnt(9)
	v_lshlrev_b32_e32 v22, 16, v124
	v_mul_f32_e32 v39, 0xbfb8aa3b, v22
	v_exp_f32_e32 v39, v39
	v_and_b32_e32 v23, 0xffff0000, v124
	v_lshlrev_b32_e32 v62, 16, v125
	v_and_b32_e32 v63, 0xffff0000, v125
	v_add_f32_e32 v39, 1.0, v39
	v_rcp_f32_e32 v58, v39
	v_mul_f32_e32 v39, 0xbfb8aa3b, v23
	v_exp_f32_e32 v39, v39
	v_lshlrev_b32_e32 v64, 16, v123
	v_and_b32_e32 v65, 0xffff0000, v123
	v_and_b32_e32 v21, 0xffff0000, v122
	v_add_f32_e32 v39, 1.0, v39
	v_rcp_f32_e32 v59, v39
	s_nop 0
	v_pk_mul_f32 v[22:23], v[58:59], v[22:23]
	v_lshlrev_b32_e32 v58, 16, v115
	v_and_b32_e32 v59, 0xffff0000, v115
	v_mul_f32_e32 v17, 0xbfb8aa3b, v64
	v_exp_f32_e32 v17, v17
	v_pk_add_f32 v[58:59], v[58:59], v[60:61]
	v_add_f32_e32 v17, 1.0, v17
	v_rcp_f32_e32 v60, v17
	v_mul_f32_e32 v17, 0xbfb8aa3b, v65
	v_exp_f32_e32 v17, v17
	s_nop 0
	v_add_f32_e32 v17, 1.0, v17
	v_rcp_f32_e32 v61, v17
	v_and_b32_e32 v17, 0xffff0000, v118
	v_pk_mul_f32 v[60:61], v[60:61], v[64:65]
	v_lshlrev_b32_e32 v64, 16, v114
	v_and_b32_e32 v65, 0xffff0000, v114
	v_lshlrev_b32_e32 v16, 16, v118
	v_lshlrev_b32_e32 v20, 16, v122
	v_mul_f32_e32 v55, 0xbfb8aa3b, v20
	v_exp_f32_e32 v55, v55
	v_pk_add_f32 v[16:17], v[64:65], v[16:17]
	v_add_f32_e32 v55, 1.0, v55
	v_add_f32_e32 v39, 0, v16
	v_add_f32_e32 v39, v17, v39
	v_rcp_f32_e32 v56, v55
	v_mul_f32_e32 v55, 0xbfb8aa3b, v21
	v_add_f32_e32 v39, v58, v39
	v_exp_f32_e32 v55, v55
	v_add_f32_e32 v39, v59, v39
	v_add_f32_e32 v39, v18, v39
	v_add_f32_e32 v39, v19, v39
	v_add_f32_e32 v39, v44, v39
	v_add_f32_e32 v55, 1.0, v55
	v_add_f32_e32 v39, v45, v39
	v_rcp_f32_e32 v57, v55
	ds_bpermute_b32 v55, v49, v39
	v_pk_mul_f32 v[20:21], v[56:57], v[20:21]
	s_waitcnt lgkmcnt(0)
	v_add_f32_e32 v39, v39, v55
	ds_bpermute_b32 v55, v50, v39
	s_waitcnt lgkmcnt(0)
	v_add_f32_e32 v39, v39, v55
	ds_bpermute_b32 v55, v51, v39
	s_waitcnt lgkmcnt(0)
	v_add_f32_e32 v39, v39, v55
	v_mul_f32_e32 v56, 0x3c800000, v39
	v_pk_add_f32 v[16:17], v[16:17], v[56:57] op_sel_hi:[1,0] neg_lo:[0,1] neg_hi:[0,1]
	v_pk_add_f32 v[58:59], v[58:59], v[56:57] op_sel_hi:[1,0] neg_lo:[0,1] neg_hi:[0,1]
	v_pk_mul_f32 v[64:65], v[16:17], v[16:17]
	v_pk_mul_f32 v[66:67], v[58:59], v[58:59]
	v_add_f32_e32 v39, v64, v65
	v_pk_add_f32 v[18:19], v[18:19], v[56:57] op_sel_hi:[1,0] neg_lo:[0,1] neg_hi:[0,1]
	v_add_f32_e32 v39, v66, v39
	v_pk_mul_f32 v[68:69], v[18:19], v[18:19]
	v_add_f32_e32 v39, v67, v39
	v_pk_add_f32 v[44:45], v[44:45], v[56:57] op_sel_hi:[1,0] neg_lo:[0,1] neg_hi:[0,1]
	v_add_f32_e32 v39, v68, v39
	v_pk_mul_f32 v[56:57], v[44:45], v[44:45]
	v_add_f32_e32 v39, v69, v39
	v_add_f32_e32 v39, v56, v39
	v_add_f32_e32 v39, v57, v39
	ds_bpermute_b32 v55, v49, v39
	s_waitcnt lgkmcnt(0)
	v_add_f32_e32 v39, v39, v55
	ds_bpermute_b32 v55, v50, v39
	s_waitcnt lgkmcnt(0)
	v_add_f32_e32 v39, v39, v55
	ds_bpermute_b32 v55, v51, v39
	s_waitcnt lgkmcnt(0)
; __device__ __forceinline__ unsigned pk2(float lo, float hi) { const f32v2_t f = {lo, hi}; const bf16v2_t b = __builtin_convertvector(f, bf16v2_t); return __builtin_bit_cast(unsigned, b); }
; __device__ __forceinline__ float siluf(float v) { return v * __builtin_amdgcn_rcpf(1.f + __expf(-v)); }
; __device__ NOINL void combine_phase(const LAS Params* lp, int l, LAS unsigned char* lds) {
;     ...
;     for (int tt = blockIdx.x; tt < ntt; tt += gridDim.x) {
;     ...
;         for (int i = 0; i < 4; ++i) {
;             const size_t row = (size_t)(row0 + 8 * w + 2 * i + (lane >> 5)); const int l32 = lane & 31;
;             float of[8], ob[8], gg[8];
;             unpack8(*(const u32x4*)(p.hbuf + row * DM + 768 + l32 * 8), of); unpack8(*(const u32x4*)(p.hyproj + row * 768 + 512 + l32 * 8), ob); unpack8(*(const u32x4*)(p.proj + row * 3072 + 2816 + l32 * 8), gg);
;             float s1 = 0.f;
; #pragma unroll
;             for (int e = 0; e < 8; ++e) { of[e] += ob[e]; s1 += of[e]; }
;             s1 += __shfl_xor(s1, 1); s1 += __shfl_xor(s1, 2); s1 += __shfl_xor(s1, 4);
;             const float mu = s1 * (1.f / 64.f); float s2 = 0.f;
; #pragma unroll
;             for (int e = 0; e < 8; ++e) { of[e] -= mu; s2 += of[e] * of[e]; }
;             s2 += __shfl_xor(s2, 1); s2 += __shfl_xor(s2, 2); s2 += __shfl_xor(s2, 4);
;             const float inv = rsqrtf(s2 * (1.f / 64.f) + 1e-6f);
;             float o[8];
; #pragma unroll
;             for (int e = 0; e < 8; ++e) o[e] = of[e] * inv * siluf(gg[e]);
;             u32x4 pk; pk.x = pk2(o[0], o[1]); pk.y = pk2(o[2], o[3]); pk.z = pk2(o[4], o[5]); pk.w = pk2(o[6], o[7]);
;             *(u32x4*)(p.hbuf + row * DM + 768 + l32 * 8) = pk;
;         }
	v_add_f32_e32 v39, v39, v55
	v_fmamk_f32 v39, v39, 0x3c800000, v211
	v_cmp_gt_f32_e32 vcc, s79, v39
	v_mul_f32_e32 v55, 0x4b800000, v39
	s_nop 0
	v_cndmask_b32_e32 v39, v39, v55, vcc
	v_rsq_f32_e32 v39, v39
	s_nop 0
	v_mul_f32_e32 v55, 0x45800000, v39
	v_cndmask_b32_e32 v56, v39, v55, vcc
	v_pk_mul_f32 v[18:19], v[18:19], v[56:57] op_sel_hi:[1,0]
	v_pk_mul_f32 v[16:17], v[16:17], v[56:57] op_sel_hi:[1,0]
	v_pk_mul_f32 v[18:19], v[22:23], v[18:19]
	v_mul_f32_e32 v22, 0xbfb8aa3b, v62
	v_mul_f32_e32 v23, 0xbfb8aa3b, v63
	v_exp_f32_e32 v22, v22
	v_exp_f32_e32 v23, v23
	v_pk_mul_f32 v[16:17], v[20:21], v[16:17]
	v_pk_mul_f32 v[20:21], v[58:59], v[56:57] op_sel_hi:[1,0]
	v_add_f32_e32 v22, 1.0, v22
	v_add_f32_e32 v23, 1.0, v23
	v_rcp_f32_e32 v22, v22
	v_rcp_f32_e32 v23, v23
	v_pk_mul_f32 v[44:45], v[44:45], v[56:57] op_sel_hi:[1,0]
	v_pk_mul_f32 v[20:21], v[60:61], v[20:21]
	v_cvt_pk_bf16_f32 v16, v16, v17
	v_pk_mul_f32 v[22:23], v[22:23], v[62:63]
	v_cvt_pk_bf16_f32 v17, v20, v21
	v_pk_mul_f32 v[22:23], v[22:23], v[44:45]
	v_cvt_pk_bf16_f32 v18, v18, v19
	v_cvt_pk_bf16_f32 v19, v22, v23
	global_store_dwordx4 v[112:113], v[16:19], off offset:1536
	s_nop 0
	v_readlane_b32 s0, v254, 33
	s_add_i32 s27, s27, s0
	s_cmp_lt_i32 s29, s6
	s_waitcnt vmcnt(9)
	v_lshlrev_b32_e32 v44, 16, v129
	v_and_b32_e32 v45, 0xffff0000, v129
	s_waitcnt vmcnt(8)
	v_lshlrev_b32_e32 v56, 16, v81
	v_and_b32_e32 v57, 0xffff0000, v81
	v_pk_add_f32 v[44:45], v[44:45], v[56:57]
	v_lshlrev_b32_e32 v56, 16, v128
	v_and_b32_e32 v57, 0xffff0000, v128
	v_lshlrev_b32_e32 v18, 16, v80
	v_and_b32_e32 v19, 0xffff0000, v80
	s_waitcnt vmcnt(7)
	v_lshlrev_b32_e32 v22, 16, v132
	v_mul_f32_e32 v37, 0xbfb8aa3b, v22
	v_exp_f32_e32 v37, v37
	v_and_b32_e32 v23, 0xffff0000, v132
	v_lshlrev_b32_e32 v58, 16, v133
	v_and_b32_e32 v59, 0xffff0000, v133
	v_add_f32_e32 v37, 1.0, v37
	v_rcp_f32_e32 v42, v37
	v_mul_f32_e32 v37, 0xbfb8aa3b, v23
	v_exp_f32_e32 v37, v37
	v_lshlrev_b32_e32 v60, 16, v131
	v_pk_add_f32 v[18:19], v[56:57], v[18:19]
	v_lshlrev_b32_e32 v56, 16, v79
	v_add_f32_e32 v37, 1.0, v37
	v_rcp_f32_e32 v43, v37
	v_and_b32_e32 v57, 0xffff0000, v79
	v_and_b32_e32 v61, 0xffff0000, v131
	v_and_b32_e32 v21, 0xffff0000, v130
	v_pk_mul_f32 v[22:23], v[42:43], v[22:23]
	v_lshlrev_b32_e32 v42, 16, v127
	v_and_b32_e32 v43, 0xffff0000, v127
	v_mul_f32_e32 v17, 0xbfb8aa3b, v60
	v_exp_f32_e32 v17, v17
	v_pk_add_f32 v[42:43], v[42:43], v[56:57]
	v_mul_f32_e32 v41, 0xbfb8aa3b, v21
	v_exp_f32_e32 v41, v41
	v_add_f32_e32 v17, 1.0, v17
	v_rcp_f32_e32 v56, v17
	v_mul_f32_e32 v17, 0xbfb8aa3b, v61
	v_exp_f32_e32 v17, v17
	v_add_f32_e32 v41, 1.0, v41
	v_rcp_f32_e32 v41, v41
	v_add_f32_e32 v17, 1.0, v17
	v_rcp_f32_e32 v57, v17
	v_and_b32_e32 v17, 0xffff0000, v78
	v_pk_mul_f32 v[56:57], v[56:57], v[60:61]
	v_lshlrev_b32_e32 v60, 16, v126
	v_and_b32_e32 v61, 0xffff0000, v126
	v_lshlrev_b32_e32 v16, 16, v78
	v_lshlrev_b32_e32 v20, 16, v130
	v_mul_f32_e32 v40, 0xbfb8aa3b, v20
	v_pk_add_f32 v[16:17], v[60:61], v[16:17]
	v_exp_f32_e32 v40, v40
	v_add_f32_e32 v37, 0, v16
	v_add_f32_e32 v37, v17, v37
	v_add_f32_e32 v37, v42, v37
	v_add_f32_e32 v40, 1.0, v40
	v_add_f32_e32 v37, v43, v37
	v_rcp_f32_e32 v40, v40
	v_add_f32_e32 v37, v18, v37
	v_add_f32_e32 v37, v19, v37
	v_add_f32_e32 v37, v44, v37
	v_add_f32_e32 v37, v45, v37
	v_pk_mul_f32 v[20:21], v[40:41], v[20:21]
	ds_bpermute_b32 v40, v49, v37
	s_waitcnt lgkmcnt(0)
	v_add_f32_e32 v37, v37, v40
	ds_bpermute_b32 v40, v50, v37
	s_waitcnt lgkmcnt(0)
	v_add_f32_e32 v37, v37, v40
	ds_bpermute_b32 v40, v51, v37
	s_waitcnt lgkmcnt(0)
	v_add_f32_e32 v37, v37, v40
	v_mul_f32_e32 v40, 0x3c800000, v37
	v_pk_add_f32 v[16:17], v[16:17], v[40:41] op_sel_hi:[1,0] neg_lo:[0,1] neg_hi:[0,1]
	v_pk_add_f32 v[42:43], v[42:43], v[40:41] op_sel_hi:[1,0] neg_lo:[0,1] neg_hi:[0,1]
	v_pk_mul_f32 v[60:61], v[16:17], v[16:17]
	v_pk_mul_f32 v[62:63], v[42:43], v[42:43]
	v_add_f32_e32 v37, v60, v61
	v_pk_add_f32 v[18:19], v[18:19], v[40:41] op_sel_hi:[1,0] neg_lo:[0,1] neg_hi:[0,1]
	v_add_f32_e32 v37, v62, v37
	v_pk_mul_f32 v[64:65], v[18:19], v[18:19]
	v_add_f32_e32 v37, v63, v37
	v_pk_add_f32 v[40:41], v[44:45], v[40:41] op_sel_hi:[1,0] neg_lo:[0,1] neg_hi:[0,1]
	v_add_f32_e32 v37, v64, v37
	v_pk_mul_f32 v[44:45], v[40:41], v[40:41]
	v_add_f32_e32 v37, v65, v37
	v_add_f32_e32 v37, v44, v37
	v_add_f32_e32 v37, v45, v37
	ds_bpermute_b32 v44, v49, v37
	s_waitcnt lgkmcnt(0)
	v_add_f32_e32 v37, v37, v44
	ds_bpermute_b32 v44, v50, v37
	s_waitcnt lgkmcnt(0)
	v_add_f32_e32 v37, v37, v44
	ds_bpermute_b32 v44, v51, v37
	s_waitcnt lgkmcnt(0)
	v_add_f32_e32 v37, v37, v44
	v_fmamk_f32 v37, v37, 0x3c800000, v211
	v_cmp_gt_f32_e32 vcc, s79, v37
	v_mul_f32_e32 v44, 0x4b800000, v37
	s_nop 0
	v_cndmask_b32_e32 v37, v37, v44, vcc
	v_rsq_f32_e32 v37, v37
	s_nop 0
	v_mul_f32_e32 v44, 0x45800000, v37
	v_cndmask_b32_e32 v44, v37, v44, vcc
	v_pk_mul_f32 v[18:19], v[18:19], v[44:45] op_sel_hi:[1,0]
	v_pk_mul_f32 v[16:17], v[16:17], v[44:45] op_sel_hi:[1,0]
	v_pk_mul_f32 v[18:19], v[22:23], v[18:19]
	v_mul_f32_e32 v22, 0xbfb8aa3b, v58
	v_mul_f32_e32 v23, 0xbfb8aa3b, v59
	v_exp_f32_e32 v22, v22
	v_exp_f32_e32 v23, v23
	v_pk_mul_f32 v[16:17], v[20:21], v[16:17]
	v_pk_mul_f32 v[20:21], v[42:43], v[44:45] op_sel_hi:[1,0]
	v_add_f32_e32 v22, 1.0, v22
	v_add_f32_e32 v23, 1.0, v23
	v_rcp_f32_e32 v22, v22
	v_rcp_f32_e32 v23, v23
	v_pk_mul_f32 v[40:41], v[40:41], v[44:45] op_sel_hi:[1,0]
	v_pk_mul_f32 v[20:21], v[56:57], v[20:21]
	v_cvt_pk_bf16_f32 v16, v16, v17
	v_pk_mul_f32 v[22:23], v[22:23], v[58:59]
	v_cvt_pk_bf16_f32 v17, v20, v21
	v_pk_mul_f32 v[22:23], v[22:23], v[40:41]
	v_cvt_pk_bf16_f32 v18, v18, v19
	v_cvt_pk_bf16_f32 v19, v22, v23
	global_store_dwordx4 v[70:71], v[16:19], off offset:1536
	s_cbranch_scc0 .LBB0_1405
